# P0: big-matrix transposes per-wave through LDS, two tiles per round when the next item is the same matrix
# speedup vs baseline: 1.0068x; 1.0031x over previous
; DI void transpose_tile(unsigned char* smem, const int tid, const float* src, int K, int N, bf16_t* dst, int ldd, int permid, int kt, int nt) {
;     float (*tile)[65] = (float (*)[65])smem;
;     const int k0 = kt * 64, n0 = nt * 64;
;     float tv[16];
; #pragma unroll
;     for (int i = 0; i < 16; ++i) {
;         int kk = i * 4 + (tid >> 6), nn = tid & 63;
;         tv[i] = (n0 + nn < N) ? src[(size_t)(k0 + kk) * N + n0 + nn] : 0.f;
;     }
; #pragma unroll
;     for (int i = 0; i < 16; ++i) tile[tid & 63][i * 4 + (tid >> 6)] = tv[i];
;     __syncthreads();
; DI void phase0(const Params& p, unsigned char* smem, const int tid, const int vb, const int nvb) {
;     ...
;     for (int it0 = vb; it0 < NTR + NADA + NS5; it0 += nvb) {
;         const int it = (it0 < NADA + NS5) ? (NTR + it0) : (it0 - NADA - NS5);
;         if (it < NTR) {
;             int id = it;
;             if (id < 1168) { transpose_tile(smem, tid, p.in[4], 1024, 4616, (bf16_t*)(ws + OFF_WIN), 1024, 1, id / 73, id % 73); continue; }
;             id -= 1168;
;             if (id < 64) {
;                 int isk = id >> 5, r = id & 31, h = r >> 3, t = r & 7;
;                 transpose_tile(smem, tid, (isk ? p.in[9] : p.in[8]) + (size_t)h * 256 * 128, 256, 128,
;                                (bf16_t*)(ws + OFF_WQK) + (size_t)h * 65536 + (isk ? 128 * 256 : 0), 256, 0, t >> 1, t & 1);
;                 continue;
;             }
;             id -= 64;
;             if (id < 256) { transpose_tile(smem, tid, p.in[11], 1024, 1024, (bf16_t*)(ws + OFF_WDN), 1024, 0, id >> 4, id & 15); continue; }
;             id -= 256;
;             if (id < 256) { transpose_tile(smem, tid, p.in[20], 512, 2048, (bf16_t*)(ws + OFF_WGL), 512, 2, id >> 5, id & 31); continue; }
;             id -= 256;
;             if (id < 256) { transpose_tile(smem, tid, p.in[21], 1024, 1024, (bf16_t*)(ws + OFF_WMX), 1024, 0, id >> 4, id & 15); continue; }
;             id -= 256;
;             if (id < 1408) { transpose_tile(smem, tid, p.in[24], 1024, 5632, (bf16_t*)(ws + OFF_WUP), 1024, 3, id / 88, id % 88); continue; }
;             id -= 1408;
;             transpose_tile(smem, tid, p.in[27], 2816, 1024, (bf16_t*)(ws + OFF_WFD), 2816, 0, id >> 4, id & 15);
.LBB0_38:
	s_andn2_saveexec_b64 s[22:23], s[22:23]
	s_cbranch_execz .LBB0_21
	s_movk_i32 s4, 0x48f
	v_cmp_lt_i32_e32 vcc, s4, v4
	s_and_saveexec_b64 s[4:5], vcc
	s_xor_b64 s[24:25], exec, s[4:5]
	s_cbranch_execz .LBB0_89
	s_movk_i32 s4, 0x4cf
	v_cmp_lt_u32_e32 vcc, s4, v4
	s_and_saveexec_b64 s[4:5], vcc
	s_xor_b64 s[26:27], exec, s[4:5]
	s_cbranch_execz .LBB0_84
	s_movk_i32 s4, 0x5cf
	v_cmp_lt_u32_e32 vcc, s4, v4
	s_and_saveexec_b64 s[4:5], vcc
	s_xor_b64 s[28:29], exec, s[4:5]
	s_cbranch_execz .LBB0_79
	s_movk_i32 s4, 0x6cf
	v_cmp_lt_u32_e32 vcc, s4, v4
	s_and_saveexec_b64 s[4:5], vcc
	s_xor_b64 s[30:31], exec, s[4:5]
	s_cbranch_execz .LBB0_66
	s_movk_i32 s4, 0x7cf
	v_cmp_lt_u32_e32 vcc, s4, v4
	s_and_saveexec_b64 s[4:5], vcc
	s_xor_b64 s[34:35], exec, s[4:5]
	s_cbranch_execz .LBB0_61
	s_movk_i32 s4, 0xd4f
	v_cmp_lt_u32_e32 vcc, s4, v4
	s_and_saveexec_b64 s[4:5], vcc
	s_xor_b64 s[4:5], exec, s[4:5]
	s_cbranch_execz .LBB0_48
	v_lshrrev_b32_e32 v191, 4, v64
	v_and_b32_e32 v197, 15, v64
	s_mov_b64 s[88:89], 0x4000
	v_lshlrev_b32_e32 v196, 6, v191
	v_readfirstlane_b32 s91, v4
	v_add_u32_e32 v190, 0xfffff2b0, v4
	v_and_b32_e32 v189, 15, v190
	v_lshrrev_b32_e32 v188, 4, v190
	v_lshlrev_b32_e32 v190, 6, v189
	v_lshlrev_b32_e32 v192, 6, v188
	v_lshl_add_u32 v198, v66, 4, v190
	v_add_u32_e32 v193, v192, v191
	v_mul_u32_u24_e32 v193, 0x400, v193
	v_add_lshl_u32 v193, v193, v198, 2
	v_sub_u32_e32 v193, v193, v196
	v_add_co_u32_e32 v194, vcc, v84, v193
	v_readfirstlane_b32 s92, v198
	v_add_lshl_u32 v199, v192, v64, 1
	v_addc_co_u32_e32 v195, vcc, 0, v85, vcc
	global_load_dword v164, v[194:195], off
	v_lshl_add_u64 v[194:195], v[194:195], 0, s[88:89]
	global_load_dword v165, v[194:195], off
	v_lshl_add_u64 v[194:195], v[194:195], 0, s[88:89]
	global_load_dword v166, v[194:195], off
	v_lshl_add_u64 v[194:195], v[194:195], 0, s[88:89]
	global_load_dword v167, v[194:195], off
	v_lshl_add_u64 v[194:195], v[194:195], 0, s[88:89]
	global_load_dword v168, v[194:195], off
	v_lshl_add_u64 v[194:195], v[194:195], 0, s[88:89]
	global_load_dword v169, v[194:195], off
	v_lshl_add_u64 v[194:195], v[194:195], 0, s[88:89]
	global_load_dword v170, v[194:195], off
	v_lshl_add_u64 v[194:195], v[194:195], 0, s[88:89]
	global_load_dword v171, v[194:195], off
	v_lshl_add_u64 v[194:195], v[194:195], 0, s[88:89]
	global_load_dword v172, v[194:195], off
	v_lshl_add_u64 v[194:195], v[194:195], 0, s[88:89]
	global_load_dword v173, v[194:195], off
	v_lshl_add_u64 v[194:195], v[194:195], 0, s[88:89]
	global_load_dword v174, v[194:195], off
	v_lshl_add_u64 v[194:195], v[194:195], 0, s[88:89]
	global_load_dword v175, v[194:195], off
	v_lshl_add_u64 v[194:195], v[194:195], 0, s[88:89]
	global_load_dword v176, v[194:195], off
	v_lshl_add_u64 v[194:195], v[194:195], 0, s[88:89]
	global_load_dword v177, v[194:195], off
	v_lshl_add_u64 v[194:195], v[194:195], 0, s[88:89]
	global_load_dword v178, v[194:195], off
	v_lshl_add_u64 v[194:195], v[194:195], 0, s[88:89]
	global_load_dword v179, v[194:195], off
	s_add_i32 s91, s91, 0x200
	s_mov_b32 s98, 0
	s_cmpk_gt_u32 s91, 0x100f
	s_cbranch_scc1 .Lp0t_fd_l1
	v_add_u32_e32 v224, 0xfffff4b0, v4
	v_and_b32_e32 v223, 15, v224
	v_lshrrev_b32_e32 v222, 4, v224
	v_lshlrev_b32_e32 v224, 6, v223
	v_lshlrev_b32_e32 v220, 6, v222
	v_lshl_add_u32 v226, v66, 4, v224
	v_add_u32_e32 v225, v220, v191
	v_mul_u32_u24_e32 v225, 0x400, v225
	v_add_lshl_u32 v225, v225, v226, 2
	v_sub_u32_e32 v225, v225, v196
	v_add_co_u32_e32 v216, vcc, v84, v225
	v_readfirstlane_b32 s100, v226
	v_add_lshl_u32 v221, v220, v64, 1
	v_addc_co_u32_e32 v217, vcc, 0, v85, vcc
	global_load_dword v200, v[216:217], off
	v_lshl_add_u64 v[216:217], v[216:217], 0, s[88:89]
	global_load_dword v201, v[216:217], off
	v_lshl_add_u64 v[216:217], v[216:217], 0, s[88:89]
	global_load_dword v202, v[216:217], off
	v_lshl_add_u64 v[216:217], v[216:217], 0, s[88:89]
	global_load_dword v203, v[216:217], off
	v_lshl_add_u64 v[216:217], v[216:217], 0, s[88:89]
	global_load_dword v204, v[216:217], off
	v_lshl_add_u64 v[216:217], v[216:217], 0, s[88:89]
	global_load_dword v205, v[216:217], off
	v_lshl_add_u64 v[216:217], v[216:217], 0, s[88:89]
	global_load_dword v206, v[216:217], off
	v_lshl_add_u64 v[216:217], v[216:217], 0, s[88:89]
	global_load_dword v207, v[216:217], off
	v_lshl_add_u64 v[216:217], v[216:217], 0, s[88:89]
	global_load_dword v208, v[216:217], off
	v_lshl_add_u64 v[216:217], v[216:217], 0, s[88:89]
	global_load_dword v209, v[216:217], off
	v_lshl_add_u64 v[216:217], v[216:217], 0, s[88:89]
	global_load_dword v210, v[216:217], off
	v_lshl_add_u64 v[216:217], v[216:217], 0, s[88:89]
	global_load_dword v211, v[216:217], off
	v_lshl_add_u64 v[216:217], v[216:217], 0, s[88:89]
	global_load_dword v212, v[216:217], off
	v_lshl_add_u64 v[216:217], v[216:217], 0, s[88:89]
	global_load_dword v213, v[216:217], off
	v_lshl_add_u64 v[216:217], v[216:217], 0, s[88:89]
	global_load_dword v214, v[216:217], off
	v_lshl_add_u64 v[216:217], v[216:217], 0, s[88:89]
	global_load_dword v215, v[216:217], off
.Lp0t_fd_l1:
	v_lshrrev_b32_e32 v186, 8, v250
	v_mul_u32_u24_e32 v195, 0x1100, v66
	v_lshlrev_b32_e32 v186, 16, v186
	v_mul_u32_u24_e32 v187, 0x110, v197
	v_add_u32_e32 v186, v186, v195
	v_lshl_add_u32 v195, v191, 2, v187
	v_add_u32_e32 v186, 0x8010, v186
	v_lshl_add_u32 v187, v64, 2, v186
	v_add_u32_e32 v195, v195, v186
	s_cmpk_gt_u32 s91, 0x100f
	s_cbranch_scc1 .Lp0t_fd_w1
	s_waitcnt vmcnt(16)
	s_branch .Lp0t_fd_w2

; DI unsigned short f2bf(float x) { return (unsigned short)(pk2(x, 0.f) & 0xffffu); }
; DI void transpose_tile(unsigned char* smem, const int tid, const float* src, int K, int N, bf16_t* dst, int ldd, int permid, int kt, int nt) {
;     ...
; #pragma unroll 4
;     for (int i = 0; i < 16; ++i) {
;         int nn = i * 4 + (tid >> 6), kk = tid & 63;
;         int n = n0 + nn;
;         if (n < N) {
;             int row = n;
;             if (permid == 1) row = (n < 2048) ? n : ((n >= 2056) ? n - 8 : -1);
;             else if (permid == 2) row = (n < 1024) ? ((n >> 2) * 8 + (n & 3)) : (((n - 1024) >> 2) * 8 + 4 + (n & 3));
;             else if (permid == 3) row = (n < 2816) ? ((n >> 2) * 8 + (n & 3)) : (((n - 2816) >> 2) * 8 + 4 + (n & 3));
;             if (row >= 0) dst[(size_t)row * ldd + k0 + kk] = f2bf(tile[nn][kk]);
;         }
;     }
;     __syncthreads();
.Lp0t_fd_w2:
	ds_write2_b32 v195, v164, v165 offset0:0 offset1:4
	ds_write2_b32 v195, v166, v167 offset0:8 offset1:12
	ds_write2_b32 v195, v168, v169 offset0:16 offset1:20
	ds_write2_b32 v195, v170, v171 offset0:24 offset1:28
	ds_write2_b32 v195, v172, v173 offset0:32 offset1:36
	ds_write2_b32 v195, v174, v175 offset0:40 offset1:44
	ds_write2_b32 v195, v176, v177 offset0:48 offset1:52
	ds_write2_b32 v195, v178, v179 offset0:56 offset1:60
	s_waitcnt lgkmcnt(0)
	ds_read_b32 v164, v187 offset:0
	ds_read_b32 v165, v187 offset:272
	ds_read_b32 v166, v187 offset:544
	ds_read_b32 v167, v187 offset:816
	ds_read_b32 v168, v187 offset:1088
	ds_read_b32 v169, v187 offset:1360
	ds_read_b32 v170, v187 offset:1632
	ds_read_b32 v171, v187 offset:1904
	ds_read_b32 v172, v187 offset:2176
	ds_read_b32 v173, v187 offset:2448
	ds_read_b32 v174, v187 offset:2720
	ds_read_b32 v175, v187 offset:2992
	ds_read_b32 v176, v187 offset:3264
	ds_read_b32 v177, v187 offset:3536
	ds_read_b32 v178, v187 offset:3808
	ds_read_b32 v179, v187 offset:4080
	s_add_i32 s93, s92, 0
	s_mov_b32 s94, s93
	s_mul_i32 s94, s94, 0x1600
	s_add_i32 s94, s94, 0x1a80000
	s_waitcnt lgkmcnt(15)
	v_cvt_pk_bf16_f32 v180, v164, v164
	v_add_u32_e32 v228, s94, v199
	global_store_short v228, v180, s[70:71]
	s_add_i32 s93, s92, 1
	s_mov_b32 s94, s93
	s_mul_i32 s94, s94, 0x1600
	s_add_i32 s94, s94, 0x1a80000
	s_waitcnt lgkmcnt(14)
	v_cvt_pk_bf16_f32 v181, v165, v165
	v_add_u32_e32 v229, s94, v199
	global_store_short v229, v181, s[70:71]
	s_add_i32 s93, s92, 2
	s_mov_b32 s94, s93
	s_mul_i32 s94, s94, 0x1600
	s_add_i32 s94, s94, 0x1a80000
	s_waitcnt lgkmcnt(13)
	v_cvt_pk_bf16_f32 v182, v166, v166
	v_add_u32_e32 v230, s94, v199
	global_store_short v230, v182, s[70:71]
	s_add_i32 s93, s92, 3
	s_mov_b32 s94, s93
	s_mul_i32 s94, s94, 0x1600
	s_add_i32 s94, s94, 0x1a80000
	s_waitcnt lgkmcnt(12)
	v_cvt_pk_bf16_f32 v183, v167, v167
	v_add_u32_e32 v231, s94, v199
	global_store_short v231, v183, s[70:71]
	s_add_i32 s93, s92, 4
	s_mov_b32 s94, s93
	s_mul_i32 s94, s94, 0x1600
	s_add_i32 s94, s94, 0x1a80000
	s_waitcnt lgkmcnt(11)
	v_cvt_pk_bf16_f32 v184, v168, v168
	v_add_u32_e32 v228, s94, v199
	global_store_short v228, v184, s[70:71]
	s_add_i32 s93, s92, 5
	s_mov_b32 s94, s93
	s_mul_i32 s94, s94, 0x1600
	s_add_i32 s94, s94, 0x1a80000
	s_waitcnt lgkmcnt(10)
	v_cvt_pk_bf16_f32 v185, v169, v169
	v_add_u32_e32 v229, s94, v199
	global_store_short v229, v185, s[70:71]
	s_add_i32 s93, s92, 6
	s_mov_b32 s94, s93
	s_mul_i32 s94, s94, 0x1600
	s_add_i32 s94, s94, 0x1a80000
	s_waitcnt lgkmcnt(9)
	v_cvt_pk_bf16_f32 v180, v170, v170
	v_add_u32_e32 v230, s94, v199
	global_store_short v230, v180, s[70:71]
	s_add_i32 s93, s92, 7
	s_mov_b32 s94, s93
	s_mul_i32 s94, s94, 0x1600
	s_add_i32 s94, s94, 0x1a80000
	s_waitcnt lgkmcnt(8)
	v_cvt_pk_bf16_f32 v181, v171, v171
	v_add_u32_e32 v231, s94, v199
	global_store_short v231, v181, s[70:71]
	s_add_i32 s93, s92, 8
	s_mov_b32 s94, s93
	s_mul_i32 s94, s94, 0x1600
	s_add_i32 s94, s94, 0x1a80000
	s_waitcnt lgkmcnt(7)
	v_cvt_pk_bf16_f32 v182, v172, v172
	v_add_u32_e32 v228, s94, v199
	global_store_short v228, v182, s[70:71]
	s_add_i32 s93, s92, 9
	s_mov_b32 s94, s93
	s_mul_i32 s94, s94, 0x1600
	s_add_i32 s94, s94, 0x1a80000
	s_waitcnt lgkmcnt(6)
	v_cvt_pk_bf16_f32 v183, v173, v173
	v_add_u32_e32 v229, s94, v199
	global_store_short v229, v183, s[70:71]
	s_add_i32 s93, s92, 10
	s_mov_b32 s94, s93
	s_mul_i32 s94, s94, 0x1600
	s_add_i32 s94, s94, 0x1a80000
	s_waitcnt lgkmcnt(5)
	v_cvt_pk_bf16_f32 v184, v174, v174
	v_add_u32_e32 v230, s94, v199
	global_store_short v230, v184, s[70:71]
	s_add_i32 s93, s92, 11
	s_mov_b32 s94, s93
	s_mul_i32 s94, s94, 0x1600
	s_add_i32 s94, s94, 0x1a80000
	s_waitcnt lgkmcnt(4)
	v_cvt_pk_bf16_f32 v185, v175, v175
	v_add_u32_e32 v231, s94, v199
	global_store_short v231, v185, s[70:71]
	s_add_i32 s93, s92, 12
	s_mov_b32 s94, s93
	s_mul_i32 s94, s94, 0x1600
	s_add_i32 s94, s94, 0x1a80000
	s_waitcnt lgkmcnt(3)
	v_cvt_pk_bf16_f32 v180, v176, v176
	v_add_u32_e32 v228, s94, v199
	global_store_short v228, v180, s[70:71]
	s_add_i32 s93, s92, 13
	s_mov_b32 s94, s93
	s_mul_i32 s94, s94, 0x1600
	s_add_i32 s94, s94, 0x1a80000
	s_waitcnt lgkmcnt(2)
	v_cvt_pk_bf16_f32 v181, v177, v177
	v_add_u32_e32 v229, s94, v199
	global_store_short v229, v181, s[70:71]
	s_add_i32 s93, s92, 14
	s_mov_b32 s94, s93
	s_mul_i32 s94, s94, 0x1600
	s_add_i32 s94, s94, 0x1a80000
	s_waitcnt lgkmcnt(1)
	v_cvt_pk_bf16_f32 v182, v178, v178
	v_add_u32_e32 v230, s94, v199
	global_store_short v230, v182, s[70:71]
	s_add_i32 s93, s92, 15
	s_mov_b32 s94, s93
	s_mul_i32 s94, s94, 0x1600
	s_add_i32 s94, s94, 0x1a80000
	s_waitcnt lgkmcnt(0)
	v_cvt_pk_bf16_f32 v183, v179, v179
	v_add_u32_e32 v231, s94, v199
	global_store_short v231, v183, s[70:71]
	s_cmpk_gt_u32 s91, 0x100f
	s_cbranch_scc1 .Lp0t_fd_done
; DI unsigned short f2bf(float x) { return (unsigned short)(pk2(x, 0.f) & 0xffffu); }
; DI void transpose_tile(unsigned char* smem, const int tid, const float* src, int K, int N, bf16_t* dst, int ldd, int permid, int kt, int nt) {
;     ...
; #pragma unroll 4
;     for (int i = 0; i < 16; ++i) {
;         int nn = i * 4 + (tid >> 6), kk = tid & 63;
;         int n = n0 + nn;
;         if (n < N) {
;             int row = n;
;             if (permid == 1) row = (n < 2048) ? n : ((n >= 2056) ? n - 8 : -1);
;             else if (permid == 2) row = (n < 1024) ? ((n >> 2) * 8 + (n & 3)) : (((n - 1024) >> 2) * 8 + 4 + (n & 3));
;             else if (permid == 3) row = (n < 2816) ? ((n >> 2) * 8 + (n & 3)) : (((n - 2816) >> 2) * 8 + 4 + (n & 3));
;             if (row >= 0) dst[(size_t)row * ldd + k0 + kk] = f2bf(tile[nn][kk]);
;         }
;     }
; DI void phase0(const Params& p, unsigned char* smem, const int tid, const int vb, const int nvb) {
;     ...
;             transpose_tile(smem, tid, p.in[27], 2816, 1024, (bf16_t*)(ws + OFF_WFD), 2816, 0, id >> 4, id & 15);
	s_waitcnt vmcnt(16)
	ds_write2_b32 v195, v200, v201 offset0:0 offset1:4
	ds_write2_b32 v195, v202, v203 offset0:8 offset1:12
	ds_write2_b32 v195, v204, v205 offset0:16 offset1:20
	ds_write2_b32 v195, v206, v207 offset0:24 offset1:28
	ds_write2_b32 v195, v208, v209 offset0:32 offset1:36
	ds_write2_b32 v195, v210, v211 offset0:40 offset1:44
	ds_write2_b32 v195, v212, v213 offset0:48 offset1:52
	ds_write2_b32 v195, v214, v215 offset0:56 offset1:60
	s_waitcnt lgkmcnt(0)
	ds_read_b32 v200, v187 offset:0
	ds_read_b32 v201, v187 offset:272
	ds_read_b32 v202, v187 offset:544
	ds_read_b32 v203, v187 offset:816
	ds_read_b32 v204, v187 offset:1088
	ds_read_b32 v205, v187 offset:1360
	ds_read_b32 v206, v187 offset:1632
	ds_read_b32 v207, v187 offset:1904
	ds_read_b32 v208, v187 offset:2176
	ds_read_b32 v209, v187 offset:2448
	ds_read_b32 v210, v187 offset:2720
	ds_read_b32 v211, v187 offset:2992
	ds_read_b32 v212, v187 offset:3264
	ds_read_b32 v213, v187 offset:3536
	ds_read_b32 v214, v187 offset:3808
	ds_read_b32 v215, v187 offset:4080
	s_add_i32 s93, s100, 0
	s_mov_b32 s94, s93
	s_mul_i32 s94, s94, 0x1600
	s_add_i32 s94, s94, 0x1a80000
	s_waitcnt lgkmcnt(15)
	v_cvt_pk_bf16_f32 v180, v200, v200
	v_add_u32_e32 v228, s94, v221
	global_store_short v228, v180, s[70:71]
	s_add_i32 s93, s100, 1
	s_mov_b32 s94, s93
	s_mul_i32 s94, s94, 0x1600
	s_add_i32 s94, s94, 0x1a80000
	s_waitcnt lgkmcnt(14)
	v_cvt_pk_bf16_f32 v181, v201, v201
	v_add_u32_e32 v229, s94, v221
	global_store_short v229, v181, s[70:71]
	s_add_i32 s93, s100, 2
	s_mov_b32 s94, s93
	s_mul_i32 s94, s94, 0x1600
	s_add_i32 s94, s94, 0x1a80000
	s_waitcnt lgkmcnt(13)
	v_cvt_pk_bf16_f32 v182, v202, v202
	v_add_u32_e32 v230, s94, v221
	global_store_short v230, v182, s[70:71]
	s_add_i32 s93, s100, 3
	s_mov_b32 s94, s93
	s_mul_i32 s94, s94, 0x1600
	s_add_i32 s94, s94, 0x1a80000
	s_waitcnt lgkmcnt(12)
	v_cvt_pk_bf16_f32 v183, v203, v203
	v_add_u32_e32 v231, s94, v221
	global_store_short v231, v183, s[70:71]
	s_add_i32 s93, s100, 4
	s_mov_b32 s94, s93
	s_mul_i32 s94, s94, 0x1600
	s_add_i32 s94, s94, 0x1a80000
	s_waitcnt lgkmcnt(11)
	v_cvt_pk_bf16_f32 v184, v204, v204
	v_add_u32_e32 v228, s94, v221
	global_store_short v228, v184, s[70:71]
	s_add_i32 s93, s100, 5
	s_mov_b32 s94, s93
	s_mul_i32 s94, s94, 0x1600
	s_add_i32 s94, s94, 0x1a80000
	s_waitcnt lgkmcnt(10)
	v_cvt_pk_bf16_f32 v185, v205, v205
	v_add_u32_e32 v229, s94, v221
	global_store_short v229, v185, s[70:71]
	s_add_i32 s93, s100, 6
	s_mov_b32 s94, s93
	s_mul_i32 s94, s94, 0x1600
	s_add_i32 s94, s94, 0x1a80000
	s_waitcnt lgkmcnt(9)
	v_cvt_pk_bf16_f32 v180, v206, v206
	v_add_u32_e32 v230, s94, v221
	global_store_short v230, v180, s[70:71]
	s_add_i32 s93, s100, 7
	s_mov_b32 s94, s93
	s_mul_i32 s94, s94, 0x1600
	s_add_i32 s94, s94, 0x1a80000
	s_waitcnt lgkmcnt(8)
	v_cvt_pk_bf16_f32 v181, v207, v207
	v_add_u32_e32 v231, s94, v221
	global_store_short v231, v181, s[70:71]
	s_add_i32 s93, s100, 8
	s_mov_b32 s94, s93
	s_mul_i32 s94, s94, 0x1600
	s_add_i32 s94, s94, 0x1a80000
	s_waitcnt lgkmcnt(7)
	v_cvt_pk_bf16_f32 v182, v208, v208
	v_add_u32_e32 v228, s94, v221
	global_store_short v228, v182, s[70:71]
	s_add_i32 s93, s100, 9
	s_mov_b32 s94, s93
	s_mul_i32 s94, s94, 0x1600
	s_add_i32 s94, s94, 0x1a80000
	s_waitcnt lgkmcnt(6)
	v_cvt_pk_bf16_f32 v183, v209, v209
	v_add_u32_e32 v229, s94, v221
	global_store_short v229, v183, s[70:71]
	s_add_i32 s93, s100, 10
	s_mov_b32 s94, s93
	s_mul_i32 s94, s94, 0x1600
	s_add_i32 s94, s94, 0x1a80000
	s_waitcnt lgkmcnt(5)
	v_cvt_pk_bf16_f32 v184, v210, v210
	v_add_u32_e32 v230, s94, v221
	global_store_short v230, v184, s[70:71]
	s_add_i32 s93, s100, 11
	s_mov_b32 s94, s93
	s_mul_i32 s94, s94, 0x1600
	s_add_i32 s94, s94, 0x1a80000
	s_waitcnt lgkmcnt(4)
	v_cvt_pk_bf16_f32 v185, v211, v211
	v_add_u32_e32 v231, s94, v221
	global_store_short v231, v185, s[70:71]
	s_add_i32 s93, s100, 12
	s_mov_b32 s94, s93
	s_mul_i32 s94, s94, 0x1600
	s_add_i32 s94, s94, 0x1a80000
	s_waitcnt lgkmcnt(3)
	v_cvt_pk_bf16_f32 v180, v212, v212
	v_add_u32_e32 v228, s94, v221
	global_store_short v228, v180, s[70:71]
	s_add_i32 s93, s100, 13
	s_mov_b32 s94, s93
	s_mul_i32 s94, s94, 0x1600
	s_add_i32 s94, s94, 0x1a80000
	s_waitcnt lgkmcnt(2)
	v_cvt_pk_bf16_f32 v181, v213, v213
	v_add_u32_e32 v229, s94, v221
	global_store_short v229, v181, s[70:71]
	s_add_i32 s93, s100, 14
	s_mov_b32 s94, s93
	s_mul_i32 s94, s94, 0x1600
	s_add_i32 s94, s94, 0x1a80000
	s_waitcnt lgkmcnt(1)
	v_cvt_pk_bf16_f32 v182, v214, v214
	v_add_u32_e32 v230, s94, v221
	global_store_short v230, v182, s[70:71]
	s_add_i32 s93, s100, 15
	s_mov_b32 s94, s93
	s_mul_i32 s94, s94, 0x1600
	s_add_i32 s94, s94, 0x1a80000
	s_waitcnt lgkmcnt(0)
	v_cvt_pk_bf16_f32 v183, v215, v215
	v_add_u32_e32 v231, s94, v221
	global_store_short v231, v183, s[70:71]
	v_add_u32_e32 v67, s90, v67
	v_add_u16_e32 v117, s90, v117
; DI void transpose_tile(unsigned char* smem, const int tid, const float* src, int K, int N, bf16_t* dst, int ldd, int permid, int kt, int nt) {
;     float (*tile)[65] = (float (*)[65])smem;
;     const int k0 = kt * 64, n0 = nt * 64;
;     float tv[16];
; #pragma unroll
;     for (int i = 0; i < 16; ++i) {
;         int kk = i * 4 + (tid >> 6), nn = tid & 63;
;         tv[i] = (n0 + nn < N) ? src[(size_t)(k0 + kk) * N + n0 + nn] : 0.f;
;     }
; #pragma unroll
;     for (int i = 0; i < 16; ++i) tile[tid & 63][i * 4 + (tid >> 6)] = tv[i];
; DI void phase0(const Params& p, unsigned char* smem, const int tid, const int vb, const int nvb) {
;     ...
;             if (id < 1408) { transpose_tile(smem, tid, p.in[24], 1024, 5632, (bf16_t*)(ws + OFF_WUP), 1024, 3, id / 88, id % 88); continue; }
.Lp0t_fd_done:
.LBB0_48:
	s_andn2_saveexec_b64 s[36:37], s[4:5]
	s_cbranch_execz .LBB0_60
	v_lshrrev_b32_e32 v191, 4, v64
	v_and_b32_e32 v197, 15, v64
	s_mov_b64 s[88:89], 0x16000
	v_lshlrev_b32_e32 v196, 6, v191
	v_readfirstlane_b32 s91, v4
	v_add_u32_e32 v190, 0xfffff830, v4
	v_mul_u32_u24_e32 v188, 0x2e9, v190
	v_lshrrev_b32_e32 v188, 16, v188
	v_mul_u32_u24_e32 v189, 0x58, v188
	v_sub_u32_e32 v189, v190, v189
	v_lshlrev_b32_e32 v190, 6, v189
	v_lshlrev_b32_e32 v192, 6, v188
	v_lshl_add_u32 v198, v66, 4, v190
	v_add_u32_e32 v193, v192, v191
	v_mul_u32_u24_e32 v193, 0x1600, v193
	v_add_lshl_u32 v193, v193, v198, 2
	v_sub_u32_e32 v193, v193, v196
	v_add_co_u32_e32 v194, vcc, v86, v193
	v_readfirstlane_b32 s92, v198
	v_add_lshl_u32 v199, v192, v64, 1
	v_addc_co_u32_e32 v195, vcc, 0, v87, vcc
	global_load_dword v164, v[194:195], off
	v_lshl_add_u64 v[194:195], v[194:195], 0, s[88:89]
	global_load_dword v165, v[194:195], off
	v_lshl_add_u64 v[194:195], v[194:195], 0, s[88:89]
	global_load_dword v166, v[194:195], off
	v_lshl_add_u64 v[194:195], v[194:195], 0, s[88:89]
	global_load_dword v167, v[194:195], off
	v_lshl_add_u64 v[194:195], v[194:195], 0, s[88:89]
	global_load_dword v168, v[194:195], off
	v_lshl_add_u64 v[194:195], v[194:195], 0, s[88:89]
	global_load_dword v169, v[194:195], off
	v_lshl_add_u64 v[194:195], v[194:195], 0, s[88:89]
	global_load_dword v170, v[194:195], off
	v_lshl_add_u64 v[194:195], v[194:195], 0, s[88:89]
	global_load_dword v171, v[194:195], off
	v_lshl_add_u64 v[194:195], v[194:195], 0, s[88:89]
	global_load_dword v172, v[194:195], off
	v_lshl_add_u64 v[194:195], v[194:195], 0, s[88:89]
	global_load_dword v173, v[194:195], off
	v_lshl_add_u64 v[194:195], v[194:195], 0, s[88:89]
	global_load_dword v174, v[194:195], off
	v_lshl_add_u64 v[194:195], v[194:195], 0, s[88:89]
	global_load_dword v175, v[194:195], off
	v_lshl_add_u64 v[194:195], v[194:195], 0, s[88:89]
	global_load_dword v176, v[194:195], off
	v_lshl_add_u64 v[194:195], v[194:195], 0, s[88:89]
	global_load_dword v177, v[194:195], off
	v_lshl_add_u64 v[194:195], v[194:195], 0, s[88:89]
	global_load_dword v178, v[194:195], off
	v_lshl_add_u64 v[194:195], v[194:195], 0, s[88:89]
	global_load_dword v179, v[194:195], off
	s_add_i32 s91, s91, 0x200
	s_mov_b32 s98, 0
	s_cmpk_gt_u32 s91, 0xd4f
	s_cbranch_scc1 .Lp0t_up_l1
	v_add_u32_e32 v224, 0xfffffa30, v4
	v_mul_u32_u24_e32 v222, 0x2e9, v224
	v_lshrrev_b32_e32 v222, 16, v222
	v_mul_u32_u24_e32 v223, 0x58, v222
	v_sub_u32_e32 v223, v224, v223
	v_lshlrev_b32_e32 v224, 6, v223
	v_lshlrev_b32_e32 v220, 6, v222
	v_lshl_add_u32 v226, v66, 4, v224
	v_add_u32_e32 v225, v220, v191
	v_mul_u32_u24_e32 v225, 0x1600, v225
	v_add_lshl_u32 v225, v225, v226, 2
	v_sub_u32_e32 v225, v225, v196
	v_add_co_u32_e32 v216, vcc, v86, v225
	v_readfirstlane_b32 s100, v226
	v_add_lshl_u32 v221, v220, v64, 1
	v_addc_co_u32_e32 v217, vcc, 0, v87, vcc
	global_load_dword v200, v[216:217], off
	v_lshl_add_u64 v[216:217], v[216:217], 0, s[88:89]
	global_load_dword v201, v[216:217], off
	v_lshl_add_u64 v[216:217], v[216:217], 0, s[88:89]
	global_load_dword v202, v[216:217], off
	v_lshl_add_u64 v[216:217], v[216:217], 0, s[88:89]
	global_load_dword v203, v[216:217], off
	v_lshl_add_u64 v[216:217], v[216:217], 0, s[88:89]
	global_load_dword v204, v[216:217], off
	v_lshl_add_u64 v[216:217], v[216:217], 0, s[88:89]
	global_load_dword v205, v[216:217], off
	v_lshl_add_u64 v[216:217], v[216:217], 0, s[88:89]
	global_load_dword v206, v[216:217], off
	v_lshl_add_u64 v[216:217], v[216:217], 0, s[88:89]
	global_load_dword v207, v[216:217], off
	v_lshl_add_u64 v[216:217], v[216:217], 0, s[88:89]
	global_load_dword v208, v[216:217], off
	v_lshl_add_u64 v[216:217], v[216:217], 0, s[88:89]
	global_load_dword v209, v[216:217], off
	v_lshl_add_u64 v[216:217], v[216:217], 0, s[88:89]
	global_load_dword v210, v[216:217], off
	v_lshl_add_u64 v[216:217], v[216:217], 0, s[88:89]
	global_load_dword v211, v[216:217], off
	v_lshl_add_u64 v[216:217], v[216:217], 0, s[88:89]
	global_load_dword v212, v[216:217], off
	v_lshl_add_u64 v[216:217], v[216:217], 0, s[88:89]
	global_load_dword v213, v[216:217], off
	v_lshl_add_u64 v[216:217], v[216:217], 0, s[88:89]
	global_load_dword v214, v[216:217], off
	v_lshl_add_u64 v[216:217], v[216:217], 0, s[88:89]
	global_load_dword v215, v[216:217], off
.Lp0t_up_l1:
	v_lshrrev_b32_e32 v186, 8, v250
	v_mul_u32_u24_e32 v195, 0x1100, v66
	v_lshlrev_b32_e32 v186, 16, v186
	v_mul_u32_u24_e32 v187, 0x110, v197
	v_add_u32_e32 v186, v186, v195
	v_lshl_add_u32 v195, v191, 2, v187
	v_add_u32_e32 v186, 0x8010, v186
	v_lshl_add_u32 v187, v64, 2, v186
	v_add_u32_e32 v195, v195, v186
	s_cmpk_gt_u32 s91, 0xd4f
	s_cbranch_scc1 .Lp0t_up_w1
	s_waitcnt vmcnt(16)
	s_branch .Lp0t_up_w2

; DI unsigned short f2bf(float x) { return (unsigned short)(pk2(x, 0.f) & 0xffffu); }
; DI void transpose_tile(unsigned char* smem, const int tid, const float* src, int K, int N, bf16_t* dst, int ldd, int permid, int kt, int nt) {
;     ...
; #pragma unroll 4
;     for (int i = 0; i < 16; ++i) {
;         int nn = i * 4 + (tid >> 6), kk = tid & 63;
;         int n = n0 + nn;
;         if (n < N) {
;             int row = n;
;             if (permid == 1) row = (n < 2048) ? n : ((n >= 2056) ? n - 8 : -1);
;             else if (permid == 2) row = (n < 1024) ? ((n >> 2) * 8 + (n & 3)) : (((n - 1024) >> 2) * 8 + 4 + (n & 3));
;             else if (permid == 3) row = (n < 2816) ? ((n >> 2) * 8 + (n & 3)) : (((n - 2816) >> 2) * 8 + 4 + (n & 3));
;             if (row >= 0) dst[(size_t)row * ldd + k0 + kk] = f2bf(tile[nn][kk]);
.Lp0t_up_w2:
	ds_write2_b32 v195, v164, v165 offset0:0 offset1:4
	ds_write2_b32 v195, v166, v167 offset0:8 offset1:12
	ds_write2_b32 v195, v168, v169 offset0:16 offset1:20
	ds_write2_b32 v195, v170, v171 offset0:24 offset1:28
	ds_write2_b32 v195, v172, v173 offset0:32 offset1:36
	ds_write2_b32 v195, v174, v175 offset0:40 offset1:44
	ds_write2_b32 v195, v176, v177 offset0:48 offset1:52
	ds_write2_b32 v195, v178, v179 offset0:56 offset1:60
	s_waitcnt lgkmcnt(0)
	ds_read_b32 v164, v187 offset:0
	ds_read_b32 v165, v187 offset:272
	ds_read_b32 v166, v187 offset:544
	ds_read_b32 v167, v187 offset:816
	ds_read_b32 v168, v187 offset:1088
	ds_read_b32 v169, v187 offset:1360
	ds_read_b32 v170, v187 offset:1632
	ds_read_b32 v171, v187 offset:1904
	ds_read_b32 v172, v187 offset:2176
	ds_read_b32 v173, v187 offset:2448
	ds_read_b32 v174, v187 offset:2720
	ds_read_b32 v175, v187 offset:2992
	ds_read_b32 v176, v187 offset:3264
	ds_read_b32 v177, v187 offset:3536
	ds_read_b32 v178, v187 offset:3808
	ds_read_b32 v179, v187 offset:4080
	s_add_i32 s93, s92, 0
	s_cmpk_lt_u32 s93, 0xb00
	s_cselect_b32 s95, 0, 0xb00
	s_cselect_b32 s94, 0, 4
	s_sub_i32 s95, s93, s95
	s_lshr_b32 s93, s95, 2
	s_and_b32 s95, s95, 3
	s_lshl_b32 s93, s93, 3
	s_add_i32 s94, s94, s95
	s_add_i32 s94, s94, s93
	s_mul_i32 s94, s94, 0x800
	s_add_i32 s94, s94, 0xf80000
	s_waitcnt lgkmcnt(15)
	v_cvt_pk_bf16_f32 v180, v164, v164
	v_add_u32_e32 v228, s94, v199
	global_store_short v228, v180, s[70:71]
	s_add_i32 s93, s92, 1
	s_cmpk_lt_u32 s93, 0xb00
	s_cselect_b32 s95, 0, 0xb00
	s_cselect_b32 s94, 0, 4
	s_sub_i32 s95, s93, s95
	s_lshr_b32 s93, s95, 2
	s_and_b32 s95, s95, 3
	s_lshl_b32 s93, s93, 3
	s_add_i32 s94, s94, s95
	s_add_i32 s94, s94, s93
	s_mul_i32 s94, s94, 0x800
	s_add_i32 s94, s94, 0xf80000
	s_waitcnt lgkmcnt(14)
	v_cvt_pk_bf16_f32 v181, v165, v165
	v_add_u32_e32 v229, s94, v199
	global_store_short v229, v181, s[70:71]
	s_add_i32 s93, s92, 2
	s_cmpk_lt_u32 s93, 0xb00
	s_cselect_b32 s95, 0, 0xb00
	s_cselect_b32 s94, 0, 4
	s_sub_i32 s95, s93, s95
	s_lshr_b32 s93, s95, 2
	s_and_b32 s95, s95, 3
	s_lshl_b32 s93, s93, 3
	s_add_i32 s94, s94, s95
	s_add_i32 s94, s94, s93
	s_mul_i32 s94, s94, 0x800
	s_add_i32 s94, s94, 0xf80000
	s_waitcnt lgkmcnt(13)
	v_cvt_pk_bf16_f32 v182, v166, v166
	v_add_u32_e32 v230, s94, v199
	global_store_short v230, v182, s[70:71]
	s_add_i32 s93, s92, 3
	s_cmpk_lt_u32 s93, 0xb00
	s_cselect_b32 s95, 0, 0xb00
	s_cselect_b32 s94, 0, 4
	s_sub_i32 s95, s93, s95
	s_lshr_b32 s93, s95, 2
	s_and_b32 s95, s95, 3
	s_lshl_b32 s93, s93, 3
	s_add_i32 s94, s94, s95
	s_add_i32 s94, s94, s93
	s_mul_i32 s94, s94, 0x800
	s_add_i32 s94, s94, 0xf80000
	s_waitcnt lgkmcnt(12)
	v_cvt_pk_bf16_f32 v183, v167, v167
	v_add_u32_e32 v231, s94, v199
	global_store_short v231, v183, s[70:71]
	s_add_i32 s93, s92, 4
	s_cmpk_lt_u32 s93, 0xb00
	s_cselect_b32 s95, 0, 0xb00
	s_cselect_b32 s94, 0, 4
	s_sub_i32 s95, s93, s95
	s_lshr_b32 s93, s95, 2
	s_and_b32 s95, s95, 3
	s_lshl_b32 s93, s93, 3
	s_add_i32 s94, s94, s95
	s_add_i32 s94, s94, s93
	s_mul_i32 s94, s94, 0x800
	s_add_i32 s94, s94, 0xf80000
	s_waitcnt lgkmcnt(11)
	v_cvt_pk_bf16_f32 v184, v168, v168
	v_add_u32_e32 v228, s94, v199
	global_store_short v228, v184, s[70:71]
	s_add_i32 s93, s92, 5
	s_cmpk_lt_u32 s93, 0xb00
	s_cselect_b32 s95, 0, 0xb00
	s_cselect_b32 s94, 0, 4
	s_sub_i32 s95, s93, s95
	s_lshr_b32 s93, s95, 2
	s_and_b32 s95, s95, 3
	s_lshl_b32 s93, s93, 3
	s_add_i32 s94, s94, s95
	s_add_i32 s94, s94, s93
	s_mul_i32 s94, s94, 0x800
	s_add_i32 s94, s94, 0xf80000
	s_waitcnt lgkmcnt(10)
	v_cvt_pk_bf16_f32 v185, v169, v169
	v_add_u32_e32 v229, s94, v199
	global_store_short v229, v185, s[70:71]
	s_add_i32 s93, s92, 6
	s_cmpk_lt_u32 s93, 0xb00
	s_cselect_b32 s95, 0, 0xb00
	s_cselect_b32 s94, 0, 4
	s_sub_i32 s95, s93, s95
	s_lshr_b32 s93, s95, 2
	s_and_b32 s95, s95, 3
	s_lshl_b32 s93, s93, 3
	s_add_i32 s94, s94, s95
	s_add_i32 s94, s94, s93
	s_mul_i32 s94, s94, 0x800
	s_add_i32 s94, s94, 0xf80000
	s_waitcnt lgkmcnt(9)
	v_cvt_pk_bf16_f32 v180, v170, v170
	v_add_u32_e32 v230, s94, v199
	global_store_short v230, v180, s[70:71]
	s_add_i32 s93, s92, 7
	s_cmpk_lt_u32 s93, 0xb00
	s_cselect_b32 s95, 0, 0xb00
	s_cselect_b32 s94, 0, 4
	s_sub_i32 s95, s93, s95
	s_lshr_b32 s93, s95, 2
	s_and_b32 s95, s95, 3
	s_lshl_b32 s93, s93, 3
	s_add_i32 s94, s94, s95
	s_add_i32 s94, s94, s93
	s_mul_i32 s94, s94, 0x800
	s_add_i32 s94, s94, 0xf80000
	s_waitcnt lgkmcnt(8)
	v_cvt_pk_bf16_f32 v181, v171, v171
	v_add_u32_e32 v231, s94, v199
	global_store_short v231, v181, s[70:71]
	s_add_i32 s93, s92, 8
	s_cmpk_lt_u32 s93, 0xb00
	s_cselect_b32 s95, 0, 0xb00
	s_cselect_b32 s94, 0, 4
	s_sub_i32 s95, s93, s95
	s_lshr_b32 s93, s95, 2
	s_and_b32 s95, s95, 3
	s_lshl_b32 s93, s93, 3
	s_add_i32 s94, s94, s95
	s_add_i32 s94, s94, s93
	s_mul_i32 s94, s94, 0x800
	s_add_i32 s94, s94, 0xf80000
	s_waitcnt lgkmcnt(7)
	v_cvt_pk_bf16_f32 v182, v172, v172
	v_add_u32_e32 v228, s94, v199
	global_store_short v228, v182, s[70:71]
	s_add_i32 s93, s92, 9
	s_cmpk_lt_u32 s93, 0xb00
	s_cselect_b32 s95, 0, 0xb00
	s_cselect_b32 s94, 0, 4
	s_sub_i32 s95, s93, s95
	s_lshr_b32 s93, s95, 2
	s_and_b32 s95, s95, 3
	s_lshl_b32 s93, s93, 3
	s_add_i32 s94, s94, s95
	s_add_i32 s94, s94, s93
	s_mul_i32 s94, s94, 0x800
	s_add_i32 s94, s94, 0xf80000
	s_waitcnt lgkmcnt(6)
	v_cvt_pk_bf16_f32 v183, v173, v173
	v_add_u32_e32 v229, s94, v199
	global_store_short v229, v183, s[70:71]
	s_add_i32 s93, s92, 10
	s_cmpk_lt_u32 s93, 0xb00
	s_cselect_b32 s95, 0, 0xb00
	s_cselect_b32 s94, 0, 4
	s_sub_i32 s95, s93, s95
	s_lshr_b32 s93, s95, 2
	s_and_b32 s95, s95, 3
	s_lshl_b32 s93, s93, 3
	s_add_i32 s94, s94, s95
	s_add_i32 s94, s94, s93
	s_mul_i32 s94, s94, 0x800
	s_add_i32 s94, s94, 0xf80000
	s_waitcnt lgkmcnt(5)
; DI unsigned short f2bf(float x) { return (unsigned short)(pk2(x, 0.f) & 0xffffu); }
; DI void transpose_tile(unsigned char* smem, const int tid, const float* src, int K, int N, bf16_t* dst, int ldd, int permid, int kt, int nt) {
;     ...
; #pragma unroll 4
;     for (int i = 0; i < 16; ++i) {
;         int nn = i * 4 + (tid >> 6), kk = tid & 63;
;         int n = n0 + nn;
;         if (n < N) {
;             int row = n;
;             if (permid == 1) row = (n < 2048) ? n : ((n >= 2056) ? n - 8 : -1);
;             else if (permid == 2) row = (n < 1024) ? ((n >> 2) * 8 + (n & 3)) : (((n - 1024) >> 2) * 8 + 4 + (n & 3));
;             else if (permid == 3) row = (n < 2816) ? ((n >> 2) * 8 + (n & 3)) : (((n - 2816) >> 2) * 8 + 4 + (n & 3));
;             if (row >= 0) dst[(size_t)row * ldd + k0 + kk] = f2bf(tile[nn][kk]);
	v_cvt_pk_bf16_f32 v184, v174, v174
	v_add_u32_e32 v230, s94, v199
	global_store_short v230, v184, s[70:71]
	s_add_i32 s93, s92, 11
	s_cmpk_lt_u32 s93, 0xb00
	s_cselect_b32 s95, 0, 0xb00
	s_cselect_b32 s94, 0, 4
	s_sub_i32 s95, s93, s95
	s_lshr_b32 s93, s95, 2
	s_and_b32 s95, s95, 3
	s_lshl_b32 s93, s93, 3
	s_add_i32 s94, s94, s95
	s_add_i32 s94, s94, s93
	s_mul_i32 s94, s94, 0x800
	s_add_i32 s94, s94, 0xf80000
	s_waitcnt lgkmcnt(4)
	v_cvt_pk_bf16_f32 v185, v175, v175
	v_add_u32_e32 v231, s94, v199
	global_store_short v231, v185, s[70:71]
	s_add_i32 s93, s92, 12
	s_cmpk_lt_u32 s93, 0xb00
	s_cselect_b32 s95, 0, 0xb00
	s_cselect_b32 s94, 0, 4
	s_sub_i32 s95, s93, s95
	s_lshr_b32 s93, s95, 2
	s_and_b32 s95, s95, 3
	s_lshl_b32 s93, s93, 3
	s_add_i32 s94, s94, s95
	s_add_i32 s94, s94, s93
	s_mul_i32 s94, s94, 0x800
	s_add_i32 s94, s94, 0xf80000
	s_waitcnt lgkmcnt(3)
	v_cvt_pk_bf16_f32 v180, v176, v176
	v_add_u32_e32 v228, s94, v199
	global_store_short v228, v180, s[70:71]
	s_add_i32 s93, s92, 13
	s_cmpk_lt_u32 s93, 0xb00
	s_cselect_b32 s95, 0, 0xb00
	s_cselect_b32 s94, 0, 4
	s_sub_i32 s95, s93, s95
	s_lshr_b32 s93, s95, 2
	s_and_b32 s95, s95, 3
	s_lshl_b32 s93, s93, 3
	s_add_i32 s94, s94, s95
	s_add_i32 s94, s94, s93
	s_mul_i32 s94, s94, 0x800
	s_add_i32 s94, s94, 0xf80000
	s_waitcnt lgkmcnt(2)
	v_cvt_pk_bf16_f32 v181, v177, v177
	v_add_u32_e32 v229, s94, v199
	global_store_short v229, v181, s[70:71]
	s_add_i32 s93, s92, 14
	s_cmpk_lt_u32 s93, 0xb00
	s_cselect_b32 s95, 0, 0xb00
	s_cselect_b32 s94, 0, 4
	s_sub_i32 s95, s93, s95
	s_lshr_b32 s93, s95, 2
	s_and_b32 s95, s95, 3
	s_lshl_b32 s93, s93, 3
	s_add_i32 s94, s94, s95
	s_add_i32 s94, s94, s93
	s_mul_i32 s94, s94, 0x800
	s_add_i32 s94, s94, 0xf80000
	s_waitcnt lgkmcnt(1)
	v_cvt_pk_bf16_f32 v182, v178, v178
	v_add_u32_e32 v230, s94, v199
	global_store_short v230, v182, s[70:71]
	s_add_i32 s93, s92, 15
	s_cmpk_lt_u32 s93, 0xb00
	s_cselect_b32 s95, 0, 0xb00
	s_cselect_b32 s94, 0, 4
	s_sub_i32 s95, s93, s95
	s_lshr_b32 s93, s95, 2
	s_and_b32 s95, s95, 3
	s_lshl_b32 s93, s93, 3
	s_add_i32 s94, s94, s95
	s_add_i32 s94, s94, s93
	s_mul_i32 s94, s94, 0x800
	s_add_i32 s94, s94, 0xf80000
	s_waitcnt lgkmcnt(0)
	v_cvt_pk_bf16_f32 v183, v179, v179
	v_add_u32_e32 v231, s94, v199
	global_store_short v231, v183, s[70:71]
	s_cmpk_gt_u32 s91, 0xd4f
	s_cbranch_scc1 .Lp0t_up_done
	s_waitcnt vmcnt(16)
	ds_write2_b32 v195, v200, v201 offset0:0 offset1:4
	ds_write2_b32 v195, v202, v203 offset0:8 offset1:12
	ds_write2_b32 v195, v204, v205 offset0:16 offset1:20
	ds_write2_b32 v195, v206, v207 offset0:24 offset1:28
	ds_write2_b32 v195, v208, v209 offset0:32 offset1:36
	ds_write2_b32 v195, v210, v211 offset0:40 offset1:44
	ds_write2_b32 v195, v212, v213 offset0:48 offset1:52
	ds_write2_b32 v195, v214, v215 offset0:56 offset1:60
	s_waitcnt lgkmcnt(0)
	ds_read_b32 v200, v187 offset:0
	ds_read_b32 v201, v187 offset:272
	ds_read_b32 v202, v187 offset:544
	ds_read_b32 v203, v187 offset:816
	ds_read_b32 v204, v187 offset:1088
	ds_read_b32 v205, v187 offset:1360
	ds_read_b32 v206, v187 offset:1632
	ds_read_b32 v207, v187 offset:1904
	ds_read_b32 v208, v187 offset:2176
	ds_read_b32 v209, v187 offset:2448
	ds_read_b32 v210, v187 offset:2720
	ds_read_b32 v211, v187 offset:2992
	ds_read_b32 v212, v187 offset:3264
	ds_read_b32 v213, v187 offset:3536
	ds_read_b32 v214, v187 offset:3808
	ds_read_b32 v215, v187 offset:4080
	s_add_i32 s93, s100, 0
	s_cmpk_lt_u32 s93, 0xb00
	s_cselect_b32 s95, 0, 0xb00
	s_cselect_b32 s94, 0, 4
	s_sub_i32 s95, s93, s95
	s_lshr_b32 s93, s95, 2
	s_and_b32 s95, s95, 3
	s_lshl_b32 s93, s93, 3
	s_add_i32 s94, s94, s95
	s_add_i32 s94, s94, s93
	s_mul_i32 s94, s94, 0x800
	s_add_i32 s94, s94, 0xf80000
	s_waitcnt lgkmcnt(15)
	v_cvt_pk_bf16_f32 v180, v200, v200
	v_add_u32_e32 v228, s94, v221
	global_store_short v228, v180, s[70:71]
	s_add_i32 s93, s100, 1
	s_cmpk_lt_u32 s93, 0xb00
	s_cselect_b32 s95, 0, 0xb00
	s_cselect_b32 s94, 0, 4
	s_sub_i32 s95, s93, s95
	s_lshr_b32 s93, s95, 2
	s_and_b32 s95, s95, 3
	s_lshl_b32 s93, s93, 3
	s_add_i32 s94, s94, s95
	s_add_i32 s94, s94, s93
	s_mul_i32 s94, s94, 0x800
	s_add_i32 s94, s94, 0xf80000
	s_waitcnt lgkmcnt(14)
	v_cvt_pk_bf16_f32 v181, v201, v201
	v_add_u32_e32 v229, s94, v221
	global_store_short v229, v181, s[70:71]
	s_add_i32 s93, s100, 2
	s_cmpk_lt_u32 s93, 0xb00
	s_cselect_b32 s95, 0, 0xb00
	s_cselect_b32 s94, 0, 4
	s_sub_i32 s95, s93, s95
	s_lshr_b32 s93, s95, 2
	s_and_b32 s95, s95, 3
	s_lshl_b32 s93, s93, 3
	s_add_i32 s94, s94, s95
	s_add_i32 s94, s94, s93
	s_mul_i32 s94, s94, 0x800
	s_add_i32 s94, s94, 0xf80000
	s_waitcnt lgkmcnt(13)
	v_cvt_pk_bf16_f32 v182, v202, v202
	v_add_u32_e32 v230, s94, v221
	global_store_short v230, v182, s[70:71]
	s_add_i32 s93, s100, 3
	s_cmpk_lt_u32 s93, 0xb00
	s_cselect_b32 s95, 0, 0xb00
	s_cselect_b32 s94, 0, 4
	s_sub_i32 s95, s93, s95
	s_lshr_b32 s93, s95, 2
	s_and_b32 s95, s95, 3
	s_lshl_b32 s93, s93, 3
	s_add_i32 s94, s94, s95
	s_add_i32 s94, s94, s93
	s_mul_i32 s94, s94, 0x800
	s_add_i32 s94, s94, 0xf80000
	s_waitcnt lgkmcnt(12)
	v_cvt_pk_bf16_f32 v183, v203, v203
	v_add_u32_e32 v231, s94, v221
	global_store_short v231, v183, s[70:71]
	s_add_i32 s93, s100, 4
	s_cmpk_lt_u32 s93, 0xb00
	s_cselect_b32 s95, 0, 0xb00
	s_cselect_b32 s94, 0, 4
	s_sub_i32 s95, s93, s95
	s_lshr_b32 s93, s95, 2
	s_and_b32 s95, s95, 3
	s_lshl_b32 s93, s93, 3
	s_add_i32 s94, s94, s95
	s_add_i32 s94, s94, s93
	s_mul_i32 s94, s94, 0x800
	s_add_i32 s94, s94, 0xf80000
	s_waitcnt lgkmcnt(11)
; DI unsigned short f2bf(float x) { return (unsigned short)(pk2(x, 0.f) & 0xffffu); }
; DI void transpose_tile(unsigned char* smem, const int tid, const float* src, int K, int N, bf16_t* dst, int ldd, int permid, int kt, int nt) {
;     ...
; #pragma unroll 4
;     for (int i = 0; i < 16; ++i) {
;         int nn = i * 4 + (tid >> 6), kk = tid & 63;
;         int n = n0 + nn;
;         if (n < N) {
;             int row = n;
;             if (permid == 1) row = (n < 2048) ? n : ((n >= 2056) ? n - 8 : -1);
;             else if (permid == 2) row = (n < 1024) ? ((n >> 2) * 8 + (n & 3)) : (((n - 1024) >> 2) * 8 + 4 + (n & 3));
;             else if (permid == 3) row = (n < 2816) ? ((n >> 2) * 8 + (n & 3)) : (((n - 2816) >> 2) * 8 + 4 + (n & 3));
;             if (row >= 0) dst[(size_t)row * ldd + k0 + kk] = f2bf(tile[nn][kk]);
; DI void phase0(const Params& p, unsigned char* smem, const int tid, const int vb, const int nvb) {
;     ...
;     for (int it0 = vb; it0 < NTR + NADA + NS5; it0 += nvb) {
	v_cvt_pk_bf16_f32 v184, v204, v204
	v_add_u32_e32 v228, s94, v221
	global_store_short v228, v184, s[70:71]
	s_add_i32 s93, s100, 5
	s_cmpk_lt_u32 s93, 0xb00
	s_cselect_b32 s95, 0, 0xb00
	s_cselect_b32 s94, 0, 4
	s_sub_i32 s95, s93, s95
	s_lshr_b32 s93, s95, 2
	s_and_b32 s95, s95, 3
	s_lshl_b32 s93, s93, 3
	s_add_i32 s94, s94, s95
	s_add_i32 s94, s94, s93
	s_mul_i32 s94, s94, 0x800
	s_add_i32 s94, s94, 0xf80000
	s_waitcnt lgkmcnt(10)
	v_cvt_pk_bf16_f32 v185, v205, v205
	v_add_u32_e32 v229, s94, v221
	global_store_short v229, v185, s[70:71]
	s_add_i32 s93, s100, 6
	s_cmpk_lt_u32 s93, 0xb00
	s_cselect_b32 s95, 0, 0xb00
	s_cselect_b32 s94, 0, 4
	s_sub_i32 s95, s93, s95
	s_lshr_b32 s93, s95, 2
	s_and_b32 s95, s95, 3
	s_lshl_b32 s93, s93, 3
	s_add_i32 s94, s94, s95
	s_add_i32 s94, s94, s93
	s_mul_i32 s94, s94, 0x800
	s_add_i32 s94, s94, 0xf80000
	s_waitcnt lgkmcnt(9)
	v_cvt_pk_bf16_f32 v180, v206, v206
	v_add_u32_e32 v230, s94, v221
	global_store_short v230, v180, s[70:71]
	s_add_i32 s93, s100, 7
	s_cmpk_lt_u32 s93, 0xb00
	s_cselect_b32 s95, 0, 0xb00
	s_cselect_b32 s94, 0, 4
	s_sub_i32 s95, s93, s95
	s_lshr_b32 s93, s95, 2
	s_and_b32 s95, s95, 3
	s_lshl_b32 s93, s93, 3
	s_add_i32 s94, s94, s95
	s_add_i32 s94, s94, s93
	s_mul_i32 s94, s94, 0x800
	s_add_i32 s94, s94, 0xf80000
	s_waitcnt lgkmcnt(8)
	v_cvt_pk_bf16_f32 v181, v207, v207
	v_add_u32_e32 v231, s94, v221
	global_store_short v231, v181, s[70:71]
	s_add_i32 s93, s100, 8
	s_cmpk_lt_u32 s93, 0xb00
	s_cselect_b32 s95, 0, 0xb00
	s_cselect_b32 s94, 0, 4
	s_sub_i32 s95, s93, s95
	s_lshr_b32 s93, s95, 2
	s_and_b32 s95, s95, 3
	s_lshl_b32 s93, s93, 3
	s_add_i32 s94, s94, s95
	s_add_i32 s94, s94, s93
	s_mul_i32 s94, s94, 0x800
	s_add_i32 s94, s94, 0xf80000
	s_waitcnt lgkmcnt(7)
	v_cvt_pk_bf16_f32 v182, v208, v208
	v_add_u32_e32 v228, s94, v221
	global_store_short v228, v182, s[70:71]
	s_add_i32 s93, s100, 9
	s_cmpk_lt_u32 s93, 0xb00
	s_cselect_b32 s95, 0, 0xb00
	s_cselect_b32 s94, 0, 4
	s_sub_i32 s95, s93, s95
	s_lshr_b32 s93, s95, 2
	s_and_b32 s95, s95, 3
	s_lshl_b32 s93, s93, 3
	s_add_i32 s94, s94, s95
	s_add_i32 s94, s94, s93
	s_mul_i32 s94, s94, 0x800
	s_add_i32 s94, s94, 0xf80000
	s_waitcnt lgkmcnt(6)
	v_cvt_pk_bf16_f32 v183, v209, v209
	v_add_u32_e32 v229, s94, v221
	global_store_short v229, v183, s[70:71]
	s_add_i32 s93, s100, 10
	s_cmpk_lt_u32 s93, 0xb00
	s_cselect_b32 s95, 0, 0xb00
	s_cselect_b32 s94, 0, 4
	s_sub_i32 s95, s93, s95
	s_lshr_b32 s93, s95, 2
	s_and_b32 s95, s95, 3
	s_lshl_b32 s93, s93, 3
	s_add_i32 s94, s94, s95
	s_add_i32 s94, s94, s93
	s_mul_i32 s94, s94, 0x800
	s_add_i32 s94, s94, 0xf80000
	s_waitcnt lgkmcnt(5)
	v_cvt_pk_bf16_f32 v184, v210, v210
	v_add_u32_e32 v230, s94, v221
	global_store_short v230, v184, s[70:71]
	s_add_i32 s93, s100, 11
	s_cmpk_lt_u32 s93, 0xb00
	s_cselect_b32 s95, 0, 0xb00
	s_cselect_b32 s94, 0, 4
	s_sub_i32 s95, s93, s95
	s_lshr_b32 s93, s95, 2
	s_and_b32 s95, s95, 3
	s_lshl_b32 s93, s93, 3
	s_add_i32 s94, s94, s95
	s_add_i32 s94, s94, s93
	s_mul_i32 s94, s94, 0x800
	s_add_i32 s94, s94, 0xf80000
	s_waitcnt lgkmcnt(4)
	v_cvt_pk_bf16_f32 v185, v211, v211
	v_add_u32_e32 v231, s94, v221
	global_store_short v231, v185, s[70:71]
	s_add_i32 s93, s100, 12
	s_cmpk_lt_u32 s93, 0xb00
	s_cselect_b32 s95, 0, 0xb00
	s_cselect_b32 s94, 0, 4
	s_sub_i32 s95, s93, s95
	s_lshr_b32 s93, s95, 2
	s_and_b32 s95, s95, 3
	s_lshl_b32 s93, s93, 3
	s_add_i32 s94, s94, s95
	s_add_i32 s94, s94, s93
	s_mul_i32 s94, s94, 0x800
	s_add_i32 s94, s94, 0xf80000
	s_waitcnt lgkmcnt(3)
	v_cvt_pk_bf16_f32 v180, v212, v212
	v_add_u32_e32 v228, s94, v221
	global_store_short v228, v180, s[70:71]
	s_add_i32 s93, s100, 13
	s_cmpk_lt_u32 s93, 0xb00
	s_cselect_b32 s95, 0, 0xb00
	s_cselect_b32 s94, 0, 4
	s_sub_i32 s95, s93, s95
	s_lshr_b32 s93, s95, 2
	s_and_b32 s95, s95, 3
	s_lshl_b32 s93, s93, 3
	s_add_i32 s94, s94, s95
	s_add_i32 s94, s94, s93
	s_mul_i32 s94, s94, 0x800
	s_add_i32 s94, s94, 0xf80000
	s_waitcnt lgkmcnt(2)
	v_cvt_pk_bf16_f32 v181, v213, v213
	v_add_u32_e32 v229, s94, v221
	global_store_short v229, v181, s[70:71]
	s_add_i32 s93, s100, 14
	s_cmpk_lt_u32 s93, 0xb00
	s_cselect_b32 s95, 0, 0xb00
	s_cselect_b32 s94, 0, 4
	s_sub_i32 s95, s93, s95
	s_lshr_b32 s93, s95, 2
	s_and_b32 s95, s95, 3
	s_lshl_b32 s93, s93, 3
	s_add_i32 s94, s94, s95
	s_add_i32 s94, s94, s93
	s_mul_i32 s94, s94, 0x800
	s_add_i32 s94, s94, 0xf80000
	s_waitcnt lgkmcnt(1)
	v_cvt_pk_bf16_f32 v182, v214, v214
	v_add_u32_e32 v230, s94, v221
	global_store_short v230, v182, s[70:71]
	s_add_i32 s93, s100, 15
	s_cmpk_lt_u32 s93, 0xb00
	s_cselect_b32 s95, 0, 0xb00
	s_cselect_b32 s94, 0, 4
	s_sub_i32 s95, s93, s95
	s_lshr_b32 s93, s95, 2
	s_and_b32 s95, s95, 3
	s_lshl_b32 s93, s93, 3
	s_add_i32 s94, s94, s95
	s_add_i32 s94, s94, s93
	s_mul_i32 s94, s94, 0x800
	s_add_i32 s94, s94, 0xf80000
	s_waitcnt lgkmcnt(0)
	v_cvt_pk_bf16_f32 v183, v215, v215
	v_add_u32_e32 v231, s94, v221
	global_store_short v231, v183, s[70:71]
	v_add_u32_e32 v67, s90, v67
	v_add_u16_e32 v117, s90, v117
.Lp0t_up_done:
.LBB0_60:
	s_or_b64 exec, exec, s[36:37]

; DI void transpose_tile(unsigned char* smem, const int tid, const float* src, int K, int N, bf16_t* dst, int ldd, int permid, int kt, int nt) {
;     float (*tile)[65] = (float (*)[65])smem;
;     const int k0 = kt * 64, n0 = nt * 64;
;     float tv[16];
; #pragma unroll
;     for (int i = 0; i < 16; ++i) {
;         int kk = i * 4 + (tid >> 6), nn = tid & 63;
;         tv[i] = (n0 + nn < N) ? src[(size_t)(k0 + kk) * N + n0 + nn] : 0.f;
;     }
; #pragma unroll
;     for (int i = 0; i < 16; ++i) tile[tid & 63][i * 4 + (tid >> 6)] = tv[i];
; DI void phase0(const Params& p, unsigned char* smem, const int tid, const int vb, const int nvb) {
;     ...
;             if (id < 1168) { transpose_tile(smem, tid, p.in[4], 1024, 4616, (bf16_t*)(ws + OFF_WIN), 1024, 1, id / 73, id % 73); continue; }
.LBB0_89:
	s_andn2_saveexec_b64 s[24:25], s[24:25]
	s_cbranch_execz .LBB0_20
	v_lshrrev_b32_e32 v191, 4, v64
	v_and_b32_e32 v197, 15, v64
	s_mov_b64 s[88:89], 0x12080
	v_lshlrev_b32_e32 v196, 6, v191
	v_readfirstlane_b32 s91, v4
	s_movk_i32 s99, 0x1208
	v_add_u32_e32 v190, 0x0, v4
	v_mul_u32_u24_e32 v188, 0x382, v190
	v_lshrrev_b32_e32 v188, 16, v188
	v_mul_u32_u24_e32 v189, 0x49, v188
	v_sub_u32_e32 v189, v190, v189
	v_lshlrev_b32_e32 v190, 6, v189
	v_lshlrev_b32_e32 v192, 6, v188
	v_lshl_add_u32 v198, v66, 4, v190
	v_add_u32_e32 v193, v192, v191
	v_mul_u32_u24_e32 v193, 0x1208, v193
	v_add_lshl_u32 v193, v193, v198, 2
	v_sub_u32_e32 v193, v193, v196
	v_add_co_u32_e32 v194, vcc, v94, v193
	v_readfirstlane_b32 s92, v198
	v_add_lshl_u32 v199, v192, v64, 1
	v_addc_co_u32_e32 v195, vcc, 0, v95, vcc
	v_add_u32_e32 v193, v198, v197
	v_cmp_gt_u32_e32 vcc, s99, v193
	s_and_saveexec_b64 s[96:97], vcc
	global_load_dword v164, v[194:195], off
	v_lshl_add_u64 v[194:195], v[194:195], 0, s[88:89]
	global_load_dword v165, v[194:195], off
	v_lshl_add_u64 v[194:195], v[194:195], 0, s[88:89]
	global_load_dword v166, v[194:195], off
	v_lshl_add_u64 v[194:195], v[194:195], 0, s[88:89]
	global_load_dword v167, v[194:195], off
	v_lshl_add_u64 v[194:195], v[194:195], 0, s[88:89]
	global_load_dword v168, v[194:195], off
	v_lshl_add_u64 v[194:195], v[194:195], 0, s[88:89]
	global_load_dword v169, v[194:195], off
	v_lshl_add_u64 v[194:195], v[194:195], 0, s[88:89]
	global_load_dword v170, v[194:195], off
	v_lshl_add_u64 v[194:195], v[194:195], 0, s[88:89]
	global_load_dword v171, v[194:195], off
	v_lshl_add_u64 v[194:195], v[194:195], 0, s[88:89]
	global_load_dword v172, v[194:195], off
	v_lshl_add_u64 v[194:195], v[194:195], 0, s[88:89]
	global_load_dword v173, v[194:195], off
	v_lshl_add_u64 v[194:195], v[194:195], 0, s[88:89]
	global_load_dword v174, v[194:195], off
	v_lshl_add_u64 v[194:195], v[194:195], 0, s[88:89]
	global_load_dword v175, v[194:195], off
	v_lshl_add_u64 v[194:195], v[194:195], 0, s[88:89]
	global_load_dword v176, v[194:195], off
	v_lshl_add_u64 v[194:195], v[194:195], 0, s[88:89]
	global_load_dword v177, v[194:195], off
	v_lshl_add_u64 v[194:195], v[194:195], 0, s[88:89]
	global_load_dword v178, v[194:195], off
	v_lshl_add_u64 v[194:195], v[194:195], 0, s[88:89]
	global_load_dword v179, v[194:195], off
	s_or_b64 exec, exec, s[96:97]
	s_add_i32 s91, s91, 0x200
	s_mov_b32 s98, 0
	s_cmpk_gt_u32 s91, 0x48f
	s_cbranch_scc1 .Lp0t_in_l1
	v_add_u32_e32 v224, 0x200, v4
	v_mul_u32_u24_e32 v222, 0x382, v224
	v_lshrrev_b32_e32 v222, 16, v222
	v_mul_u32_u24_e32 v223, 0x49, v222
	v_sub_u32_e32 v223, v224, v223
	v_lshlrev_b32_e32 v224, 6, v223
	v_lshlrev_b32_e32 v220, 6, v222
	v_lshl_add_u32 v226, v66, 4, v224
	v_add_u32_e32 v225, v220, v191
	v_mul_u32_u24_e32 v225, 0x1208, v225
	v_add_lshl_u32 v225, v225, v226, 2
	v_sub_u32_e32 v225, v225, v196
	v_add_co_u32_e32 v216, vcc, v94, v225
	v_readfirstlane_b32 s100, v226
	v_add_lshl_u32 v221, v220, v64, 1
	v_addc_co_u32_e32 v217, vcc, 0, v95, vcc
	v_add_u32_e32 v225, v226, v197
	v_cmp_gt_u32_e32 vcc, s99, v225
	s_and_saveexec_b64 s[96:97], vcc
	global_load_dword v200, v[216:217], off
	v_lshl_add_u64 v[216:217], v[216:217], 0, s[88:89]
	global_load_dword v201, v[216:217], off
	v_lshl_add_u64 v[216:217], v[216:217], 0, s[88:89]
	global_load_dword v202, v[216:217], off
	v_lshl_add_u64 v[216:217], v[216:217], 0, s[88:89]
	global_load_dword v203, v[216:217], off
	v_lshl_add_u64 v[216:217], v[216:217], 0, s[88:89]
	global_load_dword v204, v[216:217], off
	v_lshl_add_u64 v[216:217], v[216:217], 0, s[88:89]
	global_load_dword v205, v[216:217], off
	v_lshl_add_u64 v[216:217], v[216:217], 0, s[88:89]
	global_load_dword v206, v[216:217], off
	v_lshl_add_u64 v[216:217], v[216:217], 0, s[88:89]
	global_load_dword v207, v[216:217], off
	v_lshl_add_u64 v[216:217], v[216:217], 0, s[88:89]
	global_load_dword v208, v[216:217], off
	v_lshl_add_u64 v[216:217], v[216:217], 0, s[88:89]
	global_load_dword v209, v[216:217], off
	v_lshl_add_u64 v[216:217], v[216:217], 0, s[88:89]
	global_load_dword v210, v[216:217], off
	v_lshl_add_u64 v[216:217], v[216:217], 0, s[88:89]
	global_load_dword v211, v[216:217], off
	v_lshl_add_u64 v[216:217], v[216:217], 0, s[88:89]
	global_load_dword v212, v[216:217], off
	v_lshl_add_u64 v[216:217], v[216:217], 0, s[88:89]
	global_load_dword v213, v[216:217], off
	v_lshl_add_u64 v[216:217], v[216:217], 0, s[88:89]
	global_load_dword v214, v[216:217], off
	v_lshl_add_u64 v[216:217], v[216:217], 0, s[88:89]
	global_load_dword v215, v[216:217], off
	s_or_b64 exec, exec, s[96:97]
.Lp0t_in_l1:
	v_lshrrev_b32_e32 v186, 8, v250
	v_mul_u32_u24_e32 v195, 0x1100, v66
	v_lshlrev_b32_e32 v186, 16, v186
	v_mul_u32_u24_e32 v187, 0x110, v197
	v_add_u32_e32 v186, v186, v195
	v_lshl_add_u32 v195, v191, 2, v187
	v_add_u32_e32 v186, 0x8010, v186
	v_lshl_add_u32 v187, v64, 2, v186
	v_add_u32_e32 v195, v195, v186
	s_waitcnt vmcnt(0)
	ds_write2_b32 v195, v164, v165 offset0:0 offset1:4
	ds_write2_b32 v195, v166, v167 offset0:8 offset1:12
	ds_write2_b32 v195, v168, v169 offset0:16 offset1:20
	ds_write2_b32 v195, v170, v171 offset0:24 offset1:28
	ds_write2_b32 v195, v172, v173 offset0:32 offset1:36
	ds_write2_b32 v195, v174, v175 offset0:40 offset1:44
	ds_write2_b32 v195, v176, v177 offset0:48 offset1:52
	ds_write2_b32 v195, v178, v179 offset0:56 offset1:60
	s_waitcnt lgkmcnt(0)
	ds_read_b32 v164, v187 offset:0
	ds_read_b32 v165, v187 offset:272
	ds_read_b32 v166, v187 offset:544
	ds_read_b32 v167, v187 offset:816
	ds_read_b32 v168, v187 offset:1088
	ds_read_b32 v169, v187 offset:1360
	ds_read_b32 v170, v187 offset:1632
	ds_read_b32 v171, v187 offset:1904
	ds_read_b32 v172, v187 offset:2176
	ds_read_b32 v173, v187 offset:2448
	ds_read_b32 v174, v187 offset:2720
	ds_read_b32 v175, v187 offset:2992
	ds_read_b32 v176, v187 offset:3264
	ds_read_b32 v177, v187 offset:3536
	ds_read_b32 v178, v187 offset:3808
	ds_read_b32 v179, v187 offset:4080
	s_add_i32 s93, s92, 0
	s_cmpk_ge_u32 s93, 0x1208
	s_cbranch_scc1 .Lp0t_ina_0
	s_add_i32 s94, s93, 0xfffff800
	s_cmp_lt_u32 s94, 8
	s_cbranch_scc1 .Lp0t_ina_0
	s_add_i32 s94, s93, -8
	s_cmpk_lt_u32 s93, 0x800
	s_cselect_b32 s94, s93, s94
	s_mul_i32 s94, s94, 0x800
	s_waitcnt lgkmcnt(15)
	v_cvt_pk_bf16_f32 v180, v164, v164
	v_add_u32_e32 v228, s94, v199
	global_store_short v228, v180, s[70:71]
; DI unsigned short f2bf(float x) { return (unsigned short)(pk2(x, 0.f) & 0xffffu); }
; DI void transpose_tile(unsigned char* smem, const int tid, const float* src, int K, int N, bf16_t* dst, int ldd, int permid, int kt, int nt) {
;     ...
; #pragma unroll 4
;     for (int i = 0; i < 16; ++i) {
;         int nn = i * 4 + (tid >> 6), kk = tid & 63;
;         int n = n0 + nn;
;         if (n < N) {
;             int row = n;
;             if (permid == 1) row = (n < 2048) ? n : ((n >= 2056) ? n - 8 : -1);
;             else if (permid == 2) row = (n < 1024) ? ((n >> 2) * 8 + (n & 3)) : (((n - 1024) >> 2) * 8 + 4 + (n & 3));
;             else if (permid == 3) row = (n < 2816) ? ((n >> 2) * 8 + (n & 3)) : (((n - 2816) >> 2) * 8 + 4 + (n & 3));
;             if (row >= 0) dst[(size_t)row * ldd + k0 + kk] = f2bf(tile[nn][kk]);
.Lp0t_ina_0:
	s_add_i32 s93, s92, 1
	s_cmpk_ge_u32 s93, 0x1208
	s_cbranch_scc1 .Lp0t_ina_1
	s_add_i32 s94, s93, 0xfffff800
	s_cmp_lt_u32 s94, 8
	s_cbranch_scc1 .Lp0t_ina_1
	s_add_i32 s94, s93, -8
	s_cmpk_lt_u32 s93, 0x800
	s_cselect_b32 s94, s93, s94
	s_mul_i32 s94, s94, 0x800
	s_waitcnt lgkmcnt(14)
	v_cvt_pk_bf16_f32 v181, v165, v165
	v_add_u32_e32 v229, s94, v199
	global_store_short v229, v181, s[70:71]
.Lp0t_ina_1:
	s_add_i32 s93, s92, 2
	s_cmpk_ge_u32 s93, 0x1208
	s_cbranch_scc1 .Lp0t_ina_2
	s_add_i32 s94, s93, 0xfffff800
	s_cmp_lt_u32 s94, 8
	s_cbranch_scc1 .Lp0t_ina_2
	s_add_i32 s94, s93, -8
	s_cmpk_lt_u32 s93, 0x800
	s_cselect_b32 s94, s93, s94
	s_mul_i32 s94, s94, 0x800
	s_waitcnt lgkmcnt(13)
	v_cvt_pk_bf16_f32 v182, v166, v166
	v_add_u32_e32 v230, s94, v199
	global_store_short v230, v182, s[70:71]
.Lp0t_ina_2:
	s_add_i32 s93, s92, 3
	s_cmpk_ge_u32 s93, 0x1208
	s_cbranch_scc1 .Lp0t_ina_3
	s_add_i32 s94, s93, 0xfffff800
	s_cmp_lt_u32 s94, 8
	s_cbranch_scc1 .Lp0t_ina_3
	s_add_i32 s94, s93, -8
	s_cmpk_lt_u32 s93, 0x800
	s_cselect_b32 s94, s93, s94
	s_mul_i32 s94, s94, 0x800
	s_waitcnt lgkmcnt(12)
	v_cvt_pk_bf16_f32 v183, v167, v167
	v_add_u32_e32 v231, s94, v199
	global_store_short v231, v183, s[70:71]
.Lp0t_ina_3:
	s_add_i32 s93, s92, 4
	s_cmpk_ge_u32 s93, 0x1208
	s_cbranch_scc1 .Lp0t_ina_4
	s_add_i32 s94, s93, 0xfffff800
	s_cmp_lt_u32 s94, 8
	s_cbranch_scc1 .Lp0t_ina_4
	s_add_i32 s94, s93, -8
	s_cmpk_lt_u32 s93, 0x800
	s_cselect_b32 s94, s93, s94
	s_mul_i32 s94, s94, 0x800
	s_waitcnt lgkmcnt(11)
	v_cvt_pk_bf16_f32 v184, v168, v168
	v_add_u32_e32 v228, s94, v199
	global_store_short v228, v184, s[70:71]
.Lp0t_ina_4:
	s_add_i32 s93, s92, 5
	s_cmpk_ge_u32 s93, 0x1208
	s_cbranch_scc1 .Lp0t_ina_5
	s_add_i32 s94, s93, 0xfffff800
	s_cmp_lt_u32 s94, 8
	s_cbranch_scc1 .Lp0t_ina_5
	s_add_i32 s94, s93, -8
	s_cmpk_lt_u32 s93, 0x800
	s_cselect_b32 s94, s93, s94
	s_mul_i32 s94, s94, 0x800
	s_waitcnt lgkmcnt(10)
	v_cvt_pk_bf16_f32 v185, v169, v169
	v_add_u32_e32 v229, s94, v199
	global_store_short v229, v185, s[70:71]
.Lp0t_ina_5:
	s_add_i32 s93, s92, 6
	s_cmpk_ge_u32 s93, 0x1208
	s_cbranch_scc1 .Lp0t_ina_6
	s_add_i32 s94, s93, 0xfffff800
	s_cmp_lt_u32 s94, 8
	s_cbranch_scc1 .Lp0t_ina_6
	s_add_i32 s94, s93, -8
	s_cmpk_lt_u32 s93, 0x800
	s_cselect_b32 s94, s93, s94
	s_mul_i32 s94, s94, 0x800
	s_waitcnt lgkmcnt(9)
	v_cvt_pk_bf16_f32 v180, v170, v170
	v_add_u32_e32 v230, s94, v199
	global_store_short v230, v180, s[70:71]
.Lp0t_ina_6:
	s_add_i32 s93, s92, 7
	s_cmpk_ge_u32 s93, 0x1208
	s_cbranch_scc1 .Lp0t_ina_7
	s_add_i32 s94, s93, 0xfffff800
	s_cmp_lt_u32 s94, 8
	s_cbranch_scc1 .Lp0t_ina_7
	s_add_i32 s94, s93, -8
	s_cmpk_lt_u32 s93, 0x800
	s_cselect_b32 s94, s93, s94
	s_mul_i32 s94, s94, 0x800
	s_waitcnt lgkmcnt(8)
	v_cvt_pk_bf16_f32 v181, v171, v171
	v_add_u32_e32 v231, s94, v199
	global_store_short v231, v181, s[70:71]
.Lp0t_ina_7:
	s_add_i32 s93, s92, 8
	s_cmpk_ge_u32 s93, 0x1208
	s_cbranch_scc1 .Lp0t_ina_8
	s_add_i32 s94, s93, 0xfffff800
	s_cmp_lt_u32 s94, 8
	s_cbranch_scc1 .Lp0t_ina_8
	s_add_i32 s94, s93, -8
	s_cmpk_lt_u32 s93, 0x800
	s_cselect_b32 s94, s93, s94
	s_mul_i32 s94, s94, 0x800
	s_waitcnt lgkmcnt(7)
	v_cvt_pk_bf16_f32 v182, v172, v172
	v_add_u32_e32 v228, s94, v199
	global_store_short v228, v182, s[70:71]
.Lp0t_ina_8:
	s_add_i32 s93, s92, 9
	s_cmpk_ge_u32 s93, 0x1208
	s_cbranch_scc1 .Lp0t_ina_9
	s_add_i32 s94, s93, 0xfffff800
	s_cmp_lt_u32 s94, 8
	s_cbranch_scc1 .Lp0t_ina_9
	s_add_i32 s94, s93, -8
	s_cmpk_lt_u32 s93, 0x800
	s_cselect_b32 s94, s93, s94
	s_mul_i32 s94, s94, 0x800
	s_waitcnt lgkmcnt(6)
	v_cvt_pk_bf16_f32 v183, v173, v173
	v_add_u32_e32 v229, s94, v199
	global_store_short v229, v183, s[70:71]
.Lp0t_ina_9:
	s_add_i32 s93, s92, 10
	s_cmpk_ge_u32 s93, 0x1208
	s_cbranch_scc1 .Lp0t_ina_10
	s_add_i32 s94, s93, 0xfffff800
	s_cmp_lt_u32 s94, 8
	s_cbranch_scc1 .Lp0t_ina_10
	s_add_i32 s94, s93, -8
	s_cmpk_lt_u32 s93, 0x800
	s_cselect_b32 s94, s93, s94
	s_mul_i32 s94, s94, 0x800
	s_waitcnt lgkmcnt(5)
	v_cvt_pk_bf16_f32 v184, v174, v174
	v_add_u32_e32 v230, s94, v199
	global_store_short v230, v184, s[70:71]
.Lp0t_ina_10:
	s_add_i32 s93, s92, 11
	s_cmpk_ge_u32 s93, 0x1208
	s_cbranch_scc1 .Lp0t_ina_11
	s_add_i32 s94, s93, 0xfffff800
	s_cmp_lt_u32 s94, 8
	s_cbranch_scc1 .Lp0t_ina_11
	s_add_i32 s94, s93, -8
	s_cmpk_lt_u32 s93, 0x800
	s_cselect_b32 s94, s93, s94
	s_mul_i32 s94, s94, 0x800
	s_waitcnt lgkmcnt(4)
	v_cvt_pk_bf16_f32 v185, v175, v175
	v_add_u32_e32 v231, s94, v199
	global_store_short v231, v185, s[70:71]
.Lp0t_ina_11:
	s_add_i32 s93, s92, 12
	s_cmpk_ge_u32 s93, 0x1208
	s_cbranch_scc1 .Lp0t_ina_12
	s_add_i32 s94, s93, 0xfffff800
	s_cmp_lt_u32 s94, 8
	s_cbranch_scc1 .Lp0t_ina_12
	s_add_i32 s94, s93, -8
	s_cmpk_lt_u32 s93, 0x800
	s_cselect_b32 s94, s93, s94
	s_mul_i32 s94, s94, 0x800
	s_waitcnt lgkmcnt(3)
	v_cvt_pk_bf16_f32 v180, v176, v176
	v_add_u32_e32 v228, s94, v199
	global_store_short v228, v180, s[70:71]
.Lp0t_ina_12:
	s_add_i32 s93, s92, 13
	s_cmpk_ge_u32 s93, 0x1208
	s_cbranch_scc1 .Lp0t_ina_13
	s_add_i32 s94, s93, 0xfffff800
	s_cmp_lt_u32 s94, 8
	s_cbranch_scc1 .Lp0t_ina_13
	s_add_i32 s94, s93, -8
	s_cmpk_lt_u32 s93, 0x800
	s_cselect_b32 s94, s93, s94
	s_mul_i32 s94, s94, 0x800
	s_waitcnt lgkmcnt(2)
	v_cvt_pk_bf16_f32 v181, v177, v177
	v_add_u32_e32 v229, s94, v199
	global_store_short v229, v181, s[70:71]
.Lp0t_ina_13:
	s_add_i32 s93, s92, 14
	s_cmpk_ge_u32 s93, 0x1208
	s_cbranch_scc1 .Lp0t_ina_14
	s_add_i32 s94, s93, 0xfffff800
	s_cmp_lt_u32 s94, 8
	s_cbranch_scc1 .Lp0t_ina_14
	s_add_i32 s94, s93, -8
	s_cmpk_lt_u32 s93, 0x800
	s_cselect_b32 s94, s93, s94
	s_mul_i32 s94, s94, 0x800
	s_waitcnt lgkmcnt(1)
	v_cvt_pk_bf16_f32 v182, v178, v178
	v_add_u32_e32 v230, s94, v199
	global_store_short v230, v182, s[70:71]
; DI unsigned short f2bf(float x) { return (unsigned short)(pk2(x, 0.f) & 0xffffu); }
; DI void transpose_tile(unsigned char* smem, const int tid, const float* src, int K, int N, bf16_t* dst, int ldd, int permid, int kt, int nt) {
;     ...
; #pragma unroll 4
;     for (int i = 0; i < 16; ++i) {
;         int nn = i * 4 + (tid >> 6), kk = tid & 63;
;         int n = n0 + nn;
;         if (n < N) {
;             int row = n;
;             if (permid == 1) row = (n < 2048) ? n : ((n >= 2056) ? n - 8 : -1);
;             else if (permid == 2) row = (n < 1024) ? ((n >> 2) * 8 + (n & 3)) : (((n - 1024) >> 2) * 8 + 4 + (n & 3));
;             else if (permid == 3) row = (n < 2816) ? ((n >> 2) * 8 + (n & 3)) : (((n - 2816) >> 2) * 8 + 4 + (n & 3));
;             if (row >= 0) dst[(size_t)row * ldd + k0 + kk] = f2bf(tile[nn][kk]);
.Lp0t_ina_14:
	s_add_i32 s93, s92, 15
	s_cmpk_ge_u32 s93, 0x1208
	s_cbranch_scc1 .Lp0t_ina_15
	s_add_i32 s94, s93, 0xfffff800
	s_cmp_lt_u32 s94, 8
	s_cbranch_scc1 .Lp0t_ina_15
	s_add_i32 s94, s93, -8
	s_cmpk_lt_u32 s93, 0x800
	s_cselect_b32 s94, s93, s94
	s_mul_i32 s94, s94, 0x800
	s_waitcnt lgkmcnt(0)
	v_cvt_pk_bf16_f32 v183, v179, v179
	v_add_u32_e32 v231, s94, v199
	global_store_short v231, v183, s[70:71]
.Lp0t_ina_15:
	s_cmpk_gt_u32 s91, 0x48f
	s_cbranch_scc1 .Lp0t_in_done
	ds_write2_b32 v195, v200, v201 offset0:0 offset1:4
	ds_write2_b32 v195, v202, v203 offset0:8 offset1:12
	ds_write2_b32 v195, v204, v205 offset0:16 offset1:20
	ds_write2_b32 v195, v206, v207 offset0:24 offset1:28
	ds_write2_b32 v195, v208, v209 offset0:32 offset1:36
	ds_write2_b32 v195, v210, v211 offset0:40 offset1:44
	ds_write2_b32 v195, v212, v213 offset0:48 offset1:52
	ds_write2_b32 v195, v214, v215 offset0:56 offset1:60
	s_waitcnt lgkmcnt(0)
	ds_read_b32 v200, v187 offset:0
	ds_read_b32 v201, v187 offset:272
	ds_read_b32 v202, v187 offset:544
	ds_read_b32 v203, v187 offset:816
	ds_read_b32 v204, v187 offset:1088
	ds_read_b32 v205, v187 offset:1360
	ds_read_b32 v206, v187 offset:1632
	ds_read_b32 v207, v187 offset:1904
	ds_read_b32 v208, v187 offset:2176
	ds_read_b32 v209, v187 offset:2448
	ds_read_b32 v210, v187 offset:2720
	ds_read_b32 v211, v187 offset:2992
	ds_read_b32 v212, v187 offset:3264
	ds_read_b32 v213, v187 offset:3536
	ds_read_b32 v214, v187 offset:3808
	ds_read_b32 v215, v187 offset:4080
	s_add_i32 s93, s100, 0
	s_cmpk_ge_u32 s93, 0x1208
	s_cbranch_scc1 .Lp0t_inb_0
	s_add_i32 s94, s93, 0xfffff800
	s_cmp_lt_u32 s94, 8
	s_cbranch_scc1 .Lp0t_inb_0
	s_add_i32 s94, s93, -8
	s_cmpk_lt_u32 s93, 0x800
	s_cselect_b32 s94, s93, s94
	s_mul_i32 s94, s94, 0x800
	s_waitcnt lgkmcnt(15)
	v_cvt_pk_bf16_f32 v180, v200, v200
	v_add_u32_e32 v228, s94, v221
	global_store_short v228, v180, s[70:71]
.Lp0t_inb_0:
	s_add_i32 s93, s100, 1
	s_cmpk_ge_u32 s93, 0x1208
	s_cbranch_scc1 .Lp0t_inb_1
	s_add_i32 s94, s93, 0xfffff800
	s_cmp_lt_u32 s94, 8
	s_cbranch_scc1 .Lp0t_inb_1
	s_add_i32 s94, s93, -8
	s_cmpk_lt_u32 s93, 0x800
	s_cselect_b32 s94, s93, s94
	s_mul_i32 s94, s94, 0x800
	s_waitcnt lgkmcnt(14)
	v_cvt_pk_bf16_f32 v181, v201, v201
	v_add_u32_e32 v229, s94, v221
	global_store_short v229, v181, s[70:71]
.Lp0t_inb_1:
	s_add_i32 s93, s100, 2
	s_cmpk_ge_u32 s93, 0x1208
	s_cbranch_scc1 .Lp0t_inb_2
	s_add_i32 s94, s93, 0xfffff800
	s_cmp_lt_u32 s94, 8
	s_cbranch_scc1 .Lp0t_inb_2
	s_add_i32 s94, s93, -8
	s_cmpk_lt_u32 s93, 0x800
	s_cselect_b32 s94, s93, s94
	s_mul_i32 s94, s94, 0x800
	s_waitcnt lgkmcnt(13)
	v_cvt_pk_bf16_f32 v182, v202, v202
	v_add_u32_e32 v230, s94, v221
	global_store_short v230, v182, s[70:71]
.Lp0t_inb_2:
	s_add_i32 s93, s100, 3
	s_cmpk_ge_u32 s93, 0x1208
	s_cbranch_scc1 .Lp0t_inb_3
	s_add_i32 s94, s93, 0xfffff800
	s_cmp_lt_u32 s94, 8
	s_cbranch_scc1 .Lp0t_inb_3
	s_add_i32 s94, s93, -8
	s_cmpk_lt_u32 s93, 0x800
	s_cselect_b32 s94, s93, s94
	s_mul_i32 s94, s94, 0x800
	s_waitcnt lgkmcnt(12)
	v_cvt_pk_bf16_f32 v183, v203, v203
	v_add_u32_e32 v231, s94, v221
	global_store_short v231, v183, s[70:71]
.Lp0t_inb_3:
	s_add_i32 s93, s100, 4
	s_cmpk_ge_u32 s93, 0x1208
	s_cbranch_scc1 .Lp0t_inb_4
	s_add_i32 s94, s93, 0xfffff800
	s_cmp_lt_u32 s94, 8
	s_cbranch_scc1 .Lp0t_inb_4
	s_add_i32 s94, s93, -8
	s_cmpk_lt_u32 s93, 0x800
	s_cselect_b32 s94, s93, s94
	s_mul_i32 s94, s94, 0x800
	s_waitcnt lgkmcnt(11)
	v_cvt_pk_bf16_f32 v184, v204, v204
	v_add_u32_e32 v228, s94, v221
	global_store_short v228, v184, s[70:71]
.Lp0t_inb_4:
	s_add_i32 s93, s100, 5
	s_cmpk_ge_u32 s93, 0x1208
	s_cbranch_scc1 .Lp0t_inb_5
	s_add_i32 s94, s93, 0xfffff800
	s_cmp_lt_u32 s94, 8
	s_cbranch_scc1 .Lp0t_inb_5
	s_add_i32 s94, s93, -8
	s_cmpk_lt_u32 s93, 0x800
	s_cselect_b32 s94, s93, s94
	s_mul_i32 s94, s94, 0x800
	s_waitcnt lgkmcnt(10)
	v_cvt_pk_bf16_f32 v185, v205, v205
	v_add_u32_e32 v229, s94, v221
	global_store_short v229, v185, s[70:71]
; DI unsigned short f2bf(float x) { return (unsigned short)(pk2(x, 0.f) & 0xffffu); }
; DI void transpose_tile(unsigned char* smem, const int tid, const float* src, int K, int N, bf16_t* dst, int ldd, int permid, int kt, int nt) {
;     ...
; #pragma unroll 4
;     for (int i = 0; i < 16; ++i) {
;         int nn = i * 4 + (tid >> 6), kk = tid & 63;
;         int n = n0 + nn;
;         if (n < N) {
;             int row = n;
;             if (permid == 1) row = (n < 2048) ? n : ((n >= 2056) ? n - 8 : -1);
;             else if (permid == 2) row = (n < 1024) ? ((n >> 2) * 8 + (n & 3)) : (((n - 1024) >> 2) * 8 + 4 + (n & 3));
;             else if (permid == 3) row = (n < 2816) ? ((n >> 2) * 8 + (n & 3)) : (((n - 2816) >> 2) * 8 + 4 + (n & 3));
;             if (row >= 0) dst[(size_t)row * ldd + k0 + kk] = f2bf(tile[nn][kk]);
; DI void phase0(const Params& p, unsigned char* smem, const int tid, const int vb, const int nvb) {
;     ...
;     for (int it0 = vb; it0 < NTR + NADA + NS5; it0 += nvb) {
.Lp0t_inb_5:
	s_add_i32 s93, s100, 6
	s_cmpk_ge_u32 s93, 0x1208
	s_cbranch_scc1 .Lp0t_inb_6
	s_add_i32 s94, s93, 0xfffff800
	s_cmp_lt_u32 s94, 8
	s_cbranch_scc1 .Lp0t_inb_6
	s_add_i32 s94, s93, -8
	s_cmpk_lt_u32 s93, 0x800
	s_cselect_b32 s94, s93, s94
	s_mul_i32 s94, s94, 0x800
	s_waitcnt lgkmcnt(9)
	v_cvt_pk_bf16_f32 v180, v206, v206
	v_add_u32_e32 v230, s94, v221
	global_store_short v230, v180, s[70:71]
.Lp0t_inb_6:
	s_add_i32 s93, s100, 7
	s_cmpk_ge_u32 s93, 0x1208
	s_cbranch_scc1 .Lp0t_inb_7
	s_add_i32 s94, s93, 0xfffff800
	s_cmp_lt_u32 s94, 8
	s_cbranch_scc1 .Lp0t_inb_7
	s_add_i32 s94, s93, -8
	s_cmpk_lt_u32 s93, 0x800
	s_cselect_b32 s94, s93, s94
	s_mul_i32 s94, s94, 0x800
	s_waitcnt lgkmcnt(8)
	v_cvt_pk_bf16_f32 v181, v207, v207
	v_add_u32_e32 v231, s94, v221
	global_store_short v231, v181, s[70:71]
.Lp0t_inb_7:
	s_add_i32 s93, s100, 8
	s_cmpk_ge_u32 s93, 0x1208
	s_cbranch_scc1 .Lp0t_inb_8
	s_add_i32 s94, s93, 0xfffff800
	s_cmp_lt_u32 s94, 8
	s_cbranch_scc1 .Lp0t_inb_8
	s_add_i32 s94, s93, -8
	s_cmpk_lt_u32 s93, 0x800
	s_cselect_b32 s94, s93, s94
	s_mul_i32 s94, s94, 0x800
	s_waitcnt lgkmcnt(7)
	v_cvt_pk_bf16_f32 v182, v208, v208
	v_add_u32_e32 v228, s94, v221
	global_store_short v228, v182, s[70:71]
.Lp0t_inb_8:
	s_add_i32 s93, s100, 9
	s_cmpk_ge_u32 s93, 0x1208
	s_cbranch_scc1 .Lp0t_inb_9
	s_add_i32 s94, s93, 0xfffff800
	s_cmp_lt_u32 s94, 8
	s_cbranch_scc1 .Lp0t_inb_9
	s_add_i32 s94, s93, -8
	s_cmpk_lt_u32 s93, 0x800
	s_cselect_b32 s94, s93, s94
	s_mul_i32 s94, s94, 0x800
	s_waitcnt lgkmcnt(6)
	v_cvt_pk_bf16_f32 v183, v209, v209
	v_add_u32_e32 v229, s94, v221
	global_store_short v229, v183, s[70:71]
.Lp0t_inb_9:
	s_add_i32 s93, s100, 10
	s_cmpk_ge_u32 s93, 0x1208
	s_cbranch_scc1 .Lp0t_inb_10
	s_add_i32 s94, s93, 0xfffff800
	s_cmp_lt_u32 s94, 8
	s_cbranch_scc1 .Lp0t_inb_10
	s_add_i32 s94, s93, -8
	s_cmpk_lt_u32 s93, 0x800
	s_cselect_b32 s94, s93, s94
	s_mul_i32 s94, s94, 0x800
	s_waitcnt lgkmcnt(5)
	v_cvt_pk_bf16_f32 v184, v210, v210
	v_add_u32_e32 v230, s94, v221
	global_store_short v230, v184, s[70:71]
.Lp0t_inb_10:
	s_add_i32 s93, s100, 11
	s_cmpk_ge_u32 s93, 0x1208
	s_cbranch_scc1 .Lp0t_inb_11
	s_add_i32 s94, s93, 0xfffff800
	s_cmp_lt_u32 s94, 8
	s_cbranch_scc1 .Lp0t_inb_11
	s_add_i32 s94, s93, -8
	s_cmpk_lt_u32 s93, 0x800
	s_cselect_b32 s94, s93, s94
	s_mul_i32 s94, s94, 0x800
	s_waitcnt lgkmcnt(4)
	v_cvt_pk_bf16_f32 v185, v211, v211
	v_add_u32_e32 v231, s94, v221
	global_store_short v231, v185, s[70:71]
.Lp0t_inb_11:
	s_add_i32 s93, s100, 12
	s_cmpk_ge_u32 s93, 0x1208
	s_cbranch_scc1 .Lp0t_inb_12
	s_add_i32 s94, s93, 0xfffff800
	s_cmp_lt_u32 s94, 8
	s_cbranch_scc1 .Lp0t_inb_12
	s_add_i32 s94, s93, -8
	s_cmpk_lt_u32 s93, 0x800
	s_cselect_b32 s94, s93, s94
	s_mul_i32 s94, s94, 0x800
	s_waitcnt lgkmcnt(3)
	v_cvt_pk_bf16_f32 v180, v212, v212
	v_add_u32_e32 v228, s94, v221
	global_store_short v228, v180, s[70:71]
.Lp0t_inb_12:
	s_add_i32 s93, s100, 13
	s_cmpk_ge_u32 s93, 0x1208
	s_cbranch_scc1 .Lp0t_inb_13
	s_add_i32 s94, s93, 0xfffff800
	s_cmp_lt_u32 s94, 8
	s_cbranch_scc1 .Lp0t_inb_13
	s_add_i32 s94, s93, -8
	s_cmpk_lt_u32 s93, 0x800
	s_cselect_b32 s94, s93, s94
	s_mul_i32 s94, s94, 0x800
	s_waitcnt lgkmcnt(2)
	v_cvt_pk_bf16_f32 v181, v213, v213
	v_add_u32_e32 v229, s94, v221
	global_store_short v229, v181, s[70:71]
.Lp0t_inb_13:
	s_add_i32 s93, s100, 14
	s_cmpk_ge_u32 s93, 0x1208
	s_cbranch_scc1 .Lp0t_inb_14
	s_add_i32 s94, s93, 0xfffff800
	s_cmp_lt_u32 s94, 8
	s_cbranch_scc1 .Lp0t_inb_14
	s_add_i32 s94, s93, -8
	s_cmpk_lt_u32 s93, 0x800
	s_cselect_b32 s94, s93, s94
	s_mul_i32 s94, s94, 0x800
	s_waitcnt lgkmcnt(1)
	v_cvt_pk_bf16_f32 v182, v214, v214
	v_add_u32_e32 v230, s94, v221
	global_store_short v230, v182, s[70:71]
.Lp0t_inb_14:
	s_add_i32 s93, s100, 15
	s_cmpk_ge_u32 s93, 0x1208
	s_cbranch_scc1 .Lp0t_inb_15
	s_add_i32 s94, s93, 0xfffff800
	s_cmp_lt_u32 s94, 8
	s_cbranch_scc1 .Lp0t_inb_15
	s_add_i32 s94, s93, -8
	s_cmpk_lt_u32 s93, 0x800
	s_cselect_b32 s94, s93, s94
	s_mul_i32 s94, s94, 0x800
	s_waitcnt lgkmcnt(0)
	v_cvt_pk_bf16_f32 v183, v215, v215
	v_add_u32_e32 v231, s94, v221
	global_store_short v231, v183, s[70:71]
.Lp0t_inb_15:
	v_add_u32_e32 v67, s90, v67
	v_add_u16_e32 v117, s90, v117
